# loop-edge edit: GEMM K-loop pointer bumps and exit test moved in front of the loop-back barrier
# baseline (speedup 1.0000x reference)
;     __host__ __device__ __forceinline__ unsigned long long nextp(int i) const { Unit u; if (!next(i, u)) return 0ull; return pack_unit(u); }
; #define PG8_STAGE(bufoff, gbase, voff) do { _Pragma("unroll") for (int _i = 0; _i < 2; ++_i) \
;         __builtin_amdgcn_global_load_lds((const unsigned*)((const char*)(gbase) + (voff)[_i]), (PG8_LAS unsigned*)(lds + (bufoff) + ldsw + _i * 8192), 16, 0, 0); } while (0)
; #define PG8_LDA(dst, b, h) do { _Pragma("unroll") for (int m = 0; m < 4; ++m) _Pragma("unroll") for (int k = 0; k < 2; ++k) dst[m][k] = *(const PG8_LAS bf16x8*)(lds + PG8_SA(b, h) + aoff + m * 2048 + k * 1024); } while (0)
; #define PG8_LDB(dst, b, h) do { _Pragma("unroll") for (int n = 0; n < 2; ++n) _Pragma("unroll") for (int k = 0; k < 2; ++k) dst[n][k] = *(const PG8_LAS bf16x8*)(lds + PG8_SB(b, h) + boff + n * 2048 + k * 1024); } while (0)
; #define PG8_WAIT_V(n) asm volatile("s_waitcnt vmcnt(" #n ")" ::: "memory")
; template <class Epi, class Sched, bool ALIGN_EPI = false, bool SP2 = false>
; __device__ __forceinline__ void gemm_phase(PG8_LAS unsigned char* lds, const Gemm g, const Sched& S, const Epi& E) {
;     ...
;         nxt = S.nextp(ui + 1); const bool has_next = (nxt != 0ull);
;         const char* nA = has_next ? (const char*)g.A + (size_t)UP_PM(nxt) * tstep + (size_t)UP_KT0(nxt) * kstep : cA; const char* nB = has_next ? (const char*)g.Bt + (size_t)UP_PN(nxt) * tstep + (size_t)UP_KT0(nxt) * kstep : cB;
;         const int nt = UP_NKT(cur);
;         for (int t = 0; t < nt; t += 2) {
;             const bool last = (t == nt - 2);
;             const char* a1 = cA + (size_t)(t + 1) * kstep;
;             const char* a2 = last ? nA : cA + (size_t)(t + 2) * kstep; const char* b2 = last ? nB : cB + (size_t)(t + 2) * kstep;
;             const char* a3 = a2 + kstep; const char* b3 = b2 + kstep;
;             if constexpr (SP2) {
;             PG8_LDB(B0, 0, 0); PG8_LDB(B1, 0, 1); PG8_SCHED; PG8_LDA(At, 0, 0); PG8_STAGE(PG8_SA(1, 1), a1 + hstep, voffA);
;             PG8_WAIT_V(8); PG8_WAIT_L(0); PG8_BAR; PG8_MMA(0, 0, At, B0); PG8_MMA(0, 1, At, B1); PG8_BAR; PG8_SCHED;
;             PG8_LDA(At, 0, 1); PG8_STAGE(PG8_SB(0, 0), b2, voffB); PG8_STAGE(PG8_SB(0, 1), b2 + hstep, voffB); PG8_STAGE(PG8_SA(0, 0), a2, voffA);
;             PG8_WAIT_V(8); PG8_WAIT_L(0); PG8_BAR; PG8_MMA(1, 0, At, B0); PG8_MMA(1, 1, At, B1); PG8_BAR; PG8_SCHED;
.LBB0_141:
	ds_read_b128 v[154:157], v150
	ds_read_b128 v[158:161], v150 offset:1024
	ds_read_b128 v[162:165], v150 offset:2048
	ds_read_b128 v[166:169], v150 offset:3072
	ds_read_b128 v[170:173], v151
	ds_read_b128 v[174:177], v151 offset:1024
	ds_read_b128 v[178:181], v151 offset:2048
	ds_read_b128 v[182:185], v151 offset:3072
	s_add_i32 s48, s26, 2
	s_add_u32 s27, s24, 0xfff80080
	s_addc_u32 s28, s25, -1
	s_cmp_eq_u32 s45, s26
	s_cselect_b32 s26, s20, s46
	s_cselect_b32 s29, s19, s28
	s_cselect_b32 s28, s18, s27
	s_cselect_b32 s27, s21, s47
	v_lshl_add_u64 v[144:145], s[24:25], 0, v[138:139]
	s_add_i32 m0, s33, 0xc000
	ds_read_b128 v[186:189], v152
	ds_read_b128 v[190:193], v152 offset:1024
	ds_read_b128 v[194:197], v152 offset:2048
	ds_read_b128 v[198:201], v152 offset:3072
	ds_read_b128 v[202:205], v152 offset:4096
	ds_read_b128 v[206:209], v152 offset:5120
	ds_read_b128 v[214:217], v152 offset:6144
	ds_read_b128 v[218:221], v152 offset:7168
	global_load_lds_dwordx4 v[144:145], off
	v_lshl_add_u64 v[144:145], s[24:25], 0, v[140:141]
	s_add_i32 m0, s33, 0xe000
	s_nop 0
	global_load_lds_dwordx4 v[144:145], off
	s_waitcnt vmcnt(8)
	s_waitcnt lgkmcnt(0)
	s_barrier
	s_setprio 1
	s_waitcnt lgkmcnt(0)
	v_mfma_f32_16x16x32_bf16 v[120:123], v[154:157], v[186:189], v[120:123]
	v_mfma_f32_16x16x32_bf16 v[112:115], v[162:165], v[186:189], v[112:115]
	v_mfma_f32_16x16x32_bf16 v[104:107], v[154:157], v[194:197], v[104:107]
	v_mfma_f32_16x16x32_bf16 v[96:99], v[162:165], v[194:197], v[96:99]
	v_mfma_f32_16x16x32_bf16 v[88:91], v[154:157], v[202:205], v[88:91]
	v_mfma_f32_16x16x32_bf16 v[80:83], v[162:165], v[202:205], v[80:83]
	v_mfma_f32_16x16x32_bf16 v[72:75], v[154:157], v[214:217], v[72:75]
	v_mfma_f32_16x16x32_bf16 v[64:67], v[162:165], v[214:217], v[64:67]
	v_mfma_f32_16x16x32_bf16 v[120:123], v[158:161], v[190:193], v[120:123]
	v_mfma_f32_16x16x32_bf16 v[112:115], v[166:169], v[190:193], v[112:115]
	v_mfma_f32_16x16x32_bf16 v[104:107], v[158:161], v[198:201], v[104:107]
	v_mfma_f32_16x16x32_bf16 v[96:99], v[166:169], v[198:201], v[96:99]
	v_mfma_f32_16x16x32_bf16 v[88:91], v[158:161], v[206:209], v[88:91]
	v_mfma_f32_16x16x32_bf16 v[80:83], v[166:169], v[206:209], v[80:83]
	v_mfma_f32_16x16x32_bf16 v[72:75], v[158:161], v[218:221], v[72:75]
	v_mfma_f32_16x16x32_bf16 v[64:67], v[166:169], v[218:221], v[64:67]
	s_setprio 0
	s_setprio 1
	v_mfma_f32_16x16x32_bf16 v[124:127], v[170:173], v[186:189], v[124:127]
	v_mfma_f32_16x16x32_bf16 v[116:119], v[178:181], v[186:189], v[116:119]
	v_mfma_f32_16x16x32_bf16 v[108:111], v[170:173], v[194:197], v[108:111]
	v_mfma_f32_16x16x32_bf16 v[100:103], v[178:181], v[194:197], v[100:103]
	v_mfma_f32_16x16x32_bf16 v[92:95], v[170:173], v[202:205], v[92:95]
	v_mfma_f32_16x16x32_bf16 v[84:87], v[178:181], v[202:205], v[84:87]
	v_mfma_f32_16x16x32_bf16 v[76:79], v[170:173], v[214:217], v[76:79]
	v_mfma_f32_16x16x32_bf16 v[68:71], v[178:181], v[214:217], v[68:71]
	v_mfma_f32_16x16x32_bf16 v[124:127], v[174:177], v[190:193], v[124:127]
	v_mfma_f32_16x16x32_bf16 v[116:119], v[182:185], v[190:193], v[116:119]
	v_mfma_f32_16x16x32_bf16 v[108:111], v[174:177], v[198:201], v[108:111]
	v_mfma_f32_16x16x32_bf16 v[100:103], v[182:185], v[198:201], v[100:103]
	v_mfma_f32_16x16x32_bf16 v[92:95], v[174:177], v[206:209], v[92:95]
	v_mfma_f32_16x16x32_bf16 v[84:87], v[182:185], v[206:209], v[84:87]
	v_mfma_f32_16x16x32_bf16 v[76:79], v[174:177], v[218:221], v[76:79]
	v_mfma_f32_16x16x32_bf16 v[68:71], v[182:185], v[218:221], v[68:71]
	s_setprio 0
	s_barrier
	s_add_i32 s49, s42, s31
	v_lshl_add_u64 v[144:145], s[26:27], 0, v[130:131]
	s_mov_b32 m0, s49
	ds_read_b128 v[186:189], v152 offset:16384
	ds_read_b128 v[190:193], v152 offset:17408
	ds_read_b128 v[194:197], v152 offset:18432
	ds_read_b128 v[198:201], v152 offset:19456
	ds_read_b128 v[202:205], v152 offset:20480
	ds_read_b128 v[206:209], v152 offset:21504
	ds_read_b128 v[214:217], v152 offset:22528
	ds_read_b128 v[218:221], v152 offset:23552
	global_load_lds_dwordx4 v[144:145], off
	s_add_i32 m0, s49, 0x2000
	s_add_u32 s50, s26, 0x80000
	v_lshl_add_u64 v[210:211], s[26:27], 0, v[134:135]
	s_addc_u32 s51, s27, 0
	s_add_i32 s49, s43, s31
	global_load_lds_dwordx4 v[210:211], off
	v_lshl_add_u64 v[222:223], s[50:51], 0, v[130:131]
	s_mov_b32 m0, s49
	v_lshl_add_u64 v[224:225], s[28:29], 0, v[132:133]
	global_load_lds_dwordx4 v[222:223], off
	v_lshl_add_u64 v[222:223], s[50:51], 0, v[134:135]
	s_add_i32 m0, s49, 0x2000
	s_nop 0
	global_load_lds_dwordx4 v[222:223], off
	v_lshl_add_u64 v[222:223], s[28:29], 0, v[128:129]
	s_mov_b32 m0, s33
	s_nop 0
	global_load_lds_dwordx4 v[222:223], off
	s_mov_b32 m0, s34
	s_nop 0
	global_load_lds_dwordx4 v[224:225], off
	s_waitcnt vmcnt(8)
	s_waitcnt lgkmcnt(0)
	s_barrier
; #define PG8_STAGE(bufoff, gbase, voff) do { _Pragma("unroll") for (int _i = 0; _i < 2; ++_i) \
;         __builtin_amdgcn_global_load_lds((const unsigned*)((const char*)(gbase) + (voff)[_i]), (PG8_LAS unsigned*)(lds + (bufoff) + ldsw + _i * 8192), 16, 0, 0); } while (0)
; #define PG8_LDA(dst, b, h) do { _Pragma("unroll") for (int m = 0; m < 4; ++m) _Pragma("unroll") for (int k = 0; k < 2; ++k) dst[m][k] = *(const PG8_LAS bf16x8*)(lds + PG8_SA(b, h) + aoff + m * 2048 + k * 1024); } while (0)
; #define PG8_LDB(dst, b, h) do { _Pragma("unroll") for (int n = 0; n < 2; ++n) _Pragma("unroll") for (int k = 0; k < 2; ++k) dst[n][k] = *(const PG8_LAS bf16x8*)(lds + PG8_SB(b, h) + boff + n * 2048 + k * 1024); } while (0)
; #define PG8_MMA(ai, bj, At, Bt) do { __builtin_amdgcn_s_setprio(1); _Pragma("unroll") for (int m = 0; m < 4; ++m) _Pragma("unroll") for (int n = 0; n < 2; ++n) _Pragma("unroll") for (int k = 0; k < 2; ++k) \
;         acc[ai][bj][m][n] = __builtin_amdgcn_mfma_f32_16x16x32_bf16(Bt[n][k], At[m][k], acc[ai][bj][m][n], 0, 0, 0); __builtin_amdgcn_s_setprio(0); } while (0)
; #define PG8_WAIT_V(n) asm volatile("s_waitcnt vmcnt(" #n ")" ::: "memory")
; #define PG8_WAIT_L(n) asm volatile("s_waitcnt lgkmcnt(" #n ")" ::: "memory")
; #define PG8_BAR __builtin_amdgcn_s_barrier()
; #define PG8_SCHED __builtin_amdgcn_sched_barrier(0)
; template <class Epi, class Sched, bool ALIGN_EPI = false, bool SP2 = false>
; __device__ __forceinline__ void gemm_phase(PG8_LAS unsigned char* lds, const Gemm g, const Sched& S, const Epi& E) {
;     ...
;             PG8_WAIT_V(8); PG8_WAIT_L(0); PG8_BAR; PG8_MMA(1, 0, At, B0); PG8_MMA(1, 1, At, B1); PG8_BAR; PG8_SCHED;
;             PG8_LDB(B0, 1, 0); PG8_LDB(B1, 1, 1); PG8_SCHED; PG8_LDA(At, 1, 0); PG8_STAGE(PG8_SA(0, 1), a2 + hstep, voffA);
;             PG8_WAIT_V(8); PG8_WAIT_L(0); PG8_BAR; PG8_MMA(0, 0, At, B0); PG8_MMA(0, 1, At, B1); PG8_BAR; PG8_SCHED;
	s_setprio 1
	s_waitcnt lgkmcnt(0)
	v_mfma_f32_16x16x32_bf16 v[56:59], v[154:157], v[186:189], v[56:59]
	v_mfma_f32_16x16x32_bf16 v[48:51], v[162:165], v[186:189], v[48:51]
	v_mfma_f32_16x16x32_bf16 v[40:43], v[154:157], v[194:197], v[40:43]
	v_mfma_f32_16x16x32_bf16 v[32:35], v[162:165], v[194:197], v[32:35]
	v_mfma_f32_16x16x32_bf16 v[24:27], v[154:157], v[202:205], v[24:27]
	v_mfma_f32_16x16x32_bf16 v[16:19], v[162:165], v[202:205], v[16:19]
	v_mfma_f32_16x16x32_bf16 v[8:11], v[154:157], v[214:217], v[8:11]
	v_mfma_f32_16x16x32_bf16 v[0:3], v[162:165], v[214:217], v[0:3]
	v_mfma_f32_16x16x32_bf16 v[56:59], v[158:161], v[190:193], v[56:59]
	v_mfma_f32_16x16x32_bf16 v[48:51], v[166:169], v[190:193], v[48:51]
	v_mfma_f32_16x16x32_bf16 v[40:43], v[158:161], v[198:201], v[40:43]
	v_mfma_f32_16x16x32_bf16 v[32:35], v[166:169], v[198:201], v[32:35]
	v_mfma_f32_16x16x32_bf16 v[24:27], v[158:161], v[206:209], v[24:27]
	v_mfma_f32_16x16x32_bf16 v[16:19], v[166:169], v[206:209], v[16:19]
	v_mfma_f32_16x16x32_bf16 v[8:11], v[158:161], v[218:221], v[8:11]
	v_mfma_f32_16x16x32_bf16 v[0:3], v[166:169], v[218:221], v[0:3]
	s_setprio 0
	s_setprio 1
	v_mfma_f32_16x16x32_bf16 v[60:63], v[170:173], v[186:189], v[60:63]
	v_mfma_f32_16x16x32_bf16 v[52:55], v[178:181], v[186:189], v[52:55]
	v_mfma_f32_16x16x32_bf16 v[44:47], v[170:173], v[194:197], v[44:47]
	v_mfma_f32_16x16x32_bf16 v[36:39], v[178:181], v[194:197], v[36:39]
	v_mfma_f32_16x16x32_bf16 v[28:31], v[170:173], v[202:205], v[28:31]
	v_mfma_f32_16x16x32_bf16 v[20:23], v[178:181], v[202:205], v[20:23]
	v_mfma_f32_16x16x32_bf16 v[12:15], v[170:173], v[214:217], v[12:15]
	v_mfma_f32_16x16x32_bf16 v[4:7], v[178:181], v[214:217], v[4:7]
	v_mfma_f32_16x16x32_bf16 v[60:63], v[174:177], v[190:193], v[60:63]
	v_mfma_f32_16x16x32_bf16 v[52:55], v[182:185], v[190:193], v[52:55]
	v_mfma_f32_16x16x32_bf16 v[44:47], v[174:177], v[198:201], v[44:47]
	v_mfma_f32_16x16x32_bf16 v[36:39], v[182:185], v[198:201], v[36:39]
	v_mfma_f32_16x16x32_bf16 v[28:31], v[174:177], v[206:209], v[28:31]
	v_mfma_f32_16x16x32_bf16 v[20:23], v[182:185], v[206:209], v[20:23]
	v_mfma_f32_16x16x32_bf16 v[12:15], v[174:177], v[218:221], v[12:15]
	v_mfma_f32_16x16x32_bf16 v[4:7], v[182:185], v[218:221], v[4:7]
	s_setprio 0
	s_barrier
	s_add_i32 s49, 0, 0x18000
	v_add_u32_e32 v136, s49, v147
	s_add_i32 s50, 0, 0x1c000
	ds_read_b128 v[154:157], v136
	ds_read_b128 v[158:161], v136 offset:1024
	ds_read_b128 v[162:165], v136 offset:2048
	ds_read_b128 v[166:169], v136 offset:3072
	v_add_u32_e32 v136, s50, v147
	ds_read_b128 v[170:173], v136
	ds_read_b128 v[174:177], v136 offset:1024
	ds_read_b128 v[178:181], v136 offset:2048
	ds_read_b128 v[182:185], v136 offset:3072
	s_add_u32 s28, s28, 0x80000
	s_addc_u32 s29, s29, 0
	s_mov_b32 m0, s35
	v_lshl_add_u64 v[226:227], s[28:29], 0, v[128:129]
	ds_read_b128 v[186:189], v152 offset:32768
	ds_read_b128 v[190:193], v152 offset:33792
	ds_read_b128 v[194:197], v152 offset:34816
	ds_read_b128 v[198:201], v152 offset:35840
	ds_read_b128 v[202:205], v152 offset:36864
	ds_read_b128 v[206:209], v152 offset:37888
	ds_read_b128 v[214:217], v152 offset:38912
	ds_read_b128 v[218:221], v152 offset:39936
	global_load_lds_dwordx4 v[226:227], off
	v_lshl_add_u64 v[226:227], s[28:29], 0, v[132:133]
	s_mov_b32 m0, s36
	s_nop 0
	global_load_lds_dwordx4 v[226:227], off
	s_waitcnt vmcnt(8)
	s_waitcnt lgkmcnt(0)
	s_barrier
	s_setprio 1
	s_waitcnt lgkmcnt(0)
	v_mfma_f32_16x16x32_bf16 v[120:123], v[154:157], v[186:189], v[120:123]
	v_mfma_f32_16x16x32_bf16 v[112:115], v[162:165], v[186:189], v[112:115]
	v_mfma_f32_16x16x32_bf16 v[104:107], v[154:157], v[194:197], v[104:107]
	v_mfma_f32_16x16x32_bf16 v[96:99], v[162:165], v[194:197], v[96:99]
	v_mfma_f32_16x16x32_bf16 v[88:91], v[154:157], v[202:205], v[88:91]
	v_mfma_f32_16x16x32_bf16 v[80:83], v[162:165], v[202:205], v[80:83]
	v_mfma_f32_16x16x32_bf16 v[72:75], v[154:157], v[214:217], v[72:75]
	v_mfma_f32_16x16x32_bf16 v[64:67], v[162:165], v[214:217], v[64:67]
	v_mfma_f32_16x16x32_bf16 v[120:123], v[158:161], v[190:193], v[120:123]
	v_mfma_f32_16x16x32_bf16 v[112:115], v[166:169], v[190:193], v[112:115]
	v_mfma_f32_16x16x32_bf16 v[104:107], v[158:161], v[198:201], v[104:107]
	v_mfma_f32_16x16x32_bf16 v[96:99], v[166:169], v[198:201], v[96:99]
	v_mfma_f32_16x16x32_bf16 v[88:91], v[158:161], v[206:209], v[88:91]
	v_mfma_f32_16x16x32_bf16 v[80:83], v[166:169], v[206:209], v[80:83]
	v_mfma_f32_16x16x32_bf16 v[72:75], v[158:161], v[218:221], v[72:75]
	v_mfma_f32_16x16x32_bf16 v[64:67], v[166:169], v[218:221], v[64:67]
	s_setprio 0
	s_setprio 1
	v_mfma_f32_16x16x32_bf16 v[124:127], v[170:173], v[186:189], v[124:127]
	v_mfma_f32_16x16x32_bf16 v[116:119], v[178:181], v[186:189], v[116:119]
	v_mfma_f32_16x16x32_bf16 v[108:111], v[170:173], v[194:197], v[108:111]
	v_mfma_f32_16x16x32_bf16 v[100:103], v[178:181], v[194:197], v[100:103]
	v_mfma_f32_16x16x32_bf16 v[92:95], v[170:173], v[202:205], v[92:95]
	v_mfma_f32_16x16x32_bf16 v[84:87], v[178:181], v[202:205], v[84:87]
	v_mfma_f32_16x16x32_bf16 v[76:79], v[170:173], v[214:217], v[76:79]
	v_mfma_f32_16x16x32_bf16 v[68:71], v[178:181], v[214:217], v[68:71]
	v_mfma_f32_16x16x32_bf16 v[124:127], v[174:177], v[190:193], v[124:127]
	v_mfma_f32_16x16x32_bf16 v[116:119], v[182:185], v[190:193], v[116:119]
	v_mfma_f32_16x16x32_bf16 v[108:111], v[174:177], v[198:201], v[108:111]
	v_mfma_f32_16x16x32_bf16 v[100:103], v[182:185], v[198:201], v[100:103]
	v_mfma_f32_16x16x32_bf16 v[92:95], v[174:177], v[206:209], v[92:95]
	v_mfma_f32_16x16x32_bf16 v[84:87], v[182:185], v[206:209], v[84:87]
	v_mfma_f32_16x16x32_bf16 v[76:79], v[174:177], v[218:221], v[76:79]
	v_mfma_f32_16x16x32_bf16 v[68:71], v[182:185], v[218:221], v[68:71]
	s_setprio 0
	s_barrier
; #define PG8_STAGE(bufoff, gbase, voff) do { _Pragma("unroll") for (int _i = 0; _i < 2; ++_i) \
;         __builtin_amdgcn_global_load_lds((const unsigned*)((const char*)(gbase) + (voff)[_i]), (PG8_LAS unsigned*)(lds + (bufoff) + ldsw + _i * 8192), 16, 0, 0); } while (0)
; #define PG8_LDA(dst, b, h) do { _Pragma("unroll") for (int m = 0; m < 4; ++m) _Pragma("unroll") for (int k = 0; k < 2; ++k) dst[m][k] = *(const PG8_LAS bf16x8*)(lds + PG8_SA(b, h) + aoff + m * 2048 + k * 1024); } while (0)
; #define PG8_MMA(ai, bj, At, Bt) do { __builtin_amdgcn_s_setprio(1); _Pragma("unroll") for (int m = 0; m < 4; ++m) _Pragma("unroll") for (int n = 0; n < 2; ++n) _Pragma("unroll") for (int k = 0; k < 2; ++k) \
;         acc[ai][bj][m][n] = __builtin_amdgcn_mfma_f32_16x16x32_bf16(Bt[n][k], At[m][k], acc[ai][bj][m][n], 0, 0, 0); __builtin_amdgcn_s_setprio(0); } while (0)
; #define PG8_WAIT_V(n) asm volatile("s_waitcnt vmcnt(" #n ")" ::: "memory")
; #define PG8_WAIT_L(n) asm volatile("s_waitcnt lgkmcnt(" #n ")" ::: "memory")
; #define PG8_BAR __builtin_amdgcn_s_barrier()
; #define PG8_SCHED __builtin_amdgcn_sched_barrier(0)
; template <class Epi, class Sched, bool ALIGN_EPI = false, bool SP2 = false>
; __device__ __forceinline__ void gemm_phase(PG8_LAS unsigned char* lds, const Gemm g, const Sched& S, const Epi& E) {
;     ...
;         for (int t = 0; t < nt; t += 2) {
;     ...
;             PG8_LDA(At, 1, 1); PG8_STAGE(PG8_SB(1, 0), b3, voffB); PG8_STAGE(PG8_SB(1, 1), b3 + hstep, voffB); PG8_STAGE(PG8_SA(1, 0), a3, voffA);
;             PG8_WAIT_V(8); PG8_WAIT_L(0); PG8_BAR; PG8_MMA(1, 0, At, B0); PG8_MMA(1, 1, At, B1); PG8_BAR; PG8_SCHED;
	s_add_i32 s28, s49, s31
	v_lshl_add_u64 v[144:145], v[144:145], 0, s[12:13]
	s_mov_b32 m0, s28
	ds_read_b128 v[186:189], v152 offset:49152
	ds_read_b128 v[190:193], v152 offset:50176
	ds_read_b128 v[194:197], v152 offset:51200
	ds_read_b128 v[198:201], v152 offset:52224
	ds_read_b128 v[202:205], v152 offset:53248
	ds_read_b128 v[206:209], v152 offset:54272
	ds_read_b128 v[214:217], v152 offset:55296
	ds_read_b128 v[218:221], v152 offset:56320
	global_load_lds_dwordx4 v[144:145], off
	s_add_i32 m0, s28, 0x2000
	s_add_u32 s26, s26, 0x80080
	v_lshl_add_u64 v[144:145], v[210:211], 0, s[12:13]
	s_addc_u32 s27, s27, 0
	s_add_i32 s28, s50, s31
	global_load_lds_dwordx4 v[144:145], off
	v_lshl_add_u64 v[144:145], s[26:27], 0, v[130:131]
	s_mov_b32 m0, s28
	s_nop 0
	global_load_lds_dwordx4 v[144:145], off
	v_lshl_add_u64 v[144:145], s[26:27], 0, v[134:135]
	s_add_i32 m0, s28, 0x2000
	s_nop 0
	global_load_lds_dwordx4 v[144:145], off
	v_lshl_add_u64 v[144:145], v[222:223], 0, s[12:13]
	s_mov_b32 m0, s38
	s_nop 0
	global_load_lds_dwordx4 v[144:145], off
	v_lshl_add_u64 v[144:145], v[224:225], 0, s[12:13]
	s_mov_b32 m0, s39
	s_nop 0
	global_load_lds_dwordx4 v[144:145], off
	s_waitcnt vmcnt(8)
	s_waitcnt lgkmcnt(0)
	s_barrier
	s_setprio 1
	s_waitcnt lgkmcnt(0)
	v_mfma_f32_16x16x32_bf16 v[56:59], v[154:157], v[186:189], v[56:59]
	v_mfma_f32_16x16x32_bf16 v[48:51], v[162:165], v[186:189], v[48:51]
	v_mfma_f32_16x16x32_bf16 v[40:43], v[154:157], v[194:197], v[40:43]
	v_mfma_f32_16x16x32_bf16 v[32:35], v[162:165], v[194:197], v[32:35]
	v_mfma_f32_16x16x32_bf16 v[24:27], v[154:157], v[202:205], v[24:27]
	v_mfma_f32_16x16x32_bf16 v[16:19], v[162:165], v[202:205], v[16:19]
	v_mfma_f32_16x16x32_bf16 v[8:11], v[154:157], v[214:217], v[8:11]
	v_mfma_f32_16x16x32_bf16 v[0:3], v[162:165], v[214:217], v[0:3]
	v_mfma_f32_16x16x32_bf16 v[56:59], v[158:161], v[190:193], v[56:59]
	v_mfma_f32_16x16x32_bf16 v[48:51], v[166:169], v[190:193], v[48:51]
	v_mfma_f32_16x16x32_bf16 v[40:43], v[158:161], v[198:201], v[40:43]
	v_mfma_f32_16x16x32_bf16 v[32:35], v[166:169], v[198:201], v[32:35]
	v_mfma_f32_16x16x32_bf16 v[24:27], v[158:161], v[206:209], v[24:27]
	v_mfma_f32_16x16x32_bf16 v[16:19], v[166:169], v[206:209], v[16:19]
	v_mfma_f32_16x16x32_bf16 v[8:11], v[158:161], v[218:221], v[8:11]
	v_mfma_f32_16x16x32_bf16 v[0:3], v[166:169], v[218:221], v[0:3]
	s_setprio 0
	s_setprio 1
	v_mfma_f32_16x16x32_bf16 v[60:63], v[170:173], v[186:189], v[60:63]
	v_mfma_f32_16x16x32_bf16 v[52:55], v[178:181], v[186:189], v[52:55]
	v_mfma_f32_16x16x32_bf16 v[44:47], v[170:173], v[194:197], v[44:47]
	v_mfma_f32_16x16x32_bf16 v[36:39], v[178:181], v[194:197], v[36:39]
	v_mfma_f32_16x16x32_bf16 v[28:31], v[170:173], v[202:205], v[28:31]
	v_mfma_f32_16x16x32_bf16 v[20:23], v[178:181], v[202:205], v[20:23]
	v_mfma_f32_16x16x32_bf16 v[12:15], v[170:173], v[214:217], v[12:15]
	v_mfma_f32_16x16x32_bf16 v[4:7], v[178:181], v[214:217], v[4:7]
	v_mfma_f32_16x16x32_bf16 v[60:63], v[174:177], v[190:193], v[60:63]
	v_mfma_f32_16x16x32_bf16 v[52:55], v[182:185], v[190:193], v[52:55]
	v_mfma_f32_16x16x32_bf16 v[44:47], v[174:177], v[198:201], v[44:47]
	v_mfma_f32_16x16x32_bf16 v[36:39], v[182:185], v[198:201], v[36:39]
	v_mfma_f32_16x16x32_bf16 v[28:31], v[174:177], v[206:209], v[28:31]
	v_mfma_f32_16x16x32_bf16 v[20:23], v[182:185], v[206:209], v[20:23]
	v_mfma_f32_16x16x32_bf16 v[12:15], v[174:177], v[218:221], v[12:15]
	v_mfma_f32_16x16x32_bf16 v[4:7], v[182:185], v[218:221], v[4:7]
	s_setprio 0
	s_add_u32 s24, s24, 0x100
	s_addc_u32 s25, s25, 0
	s_add_u32 s46, s46, 0x100
	s_addc_u32 s47, s47, 0
	s_cmp_ge_u32 s48, s23
	s_mov_b32 s26, s48
	s_barrier
	s_cbranch_scc0 .LBB0_141

; #define LAS __attribute__((address_space(3)))
; __device__ __forceinline__ int ltid() { int t = threadIdx.x; asm volatile("" : "+v"(t)); return t; }
; __device__ __forceinline__ KArgs ka_get() { KArgs p = (KArgs)__builtin_amdgcn_kernarg_segment_ptr(); asm volatile("" : "+s"(p)); return p; }
; __global__ void __launch_bounds__(512, 2) mk_fwd(Args args) {
;     ...
;     if (IN(0)) { const KArgs KA = ka_get(); const int tid = ltid(), lane = tid & 63, wave = __builtin_amdgcn_readfirstlane(tid >> 6); (void)lane; (void)wave;
;         LAS float* scr = (LAS float*)(lds + wave * 16384);
;         const int gw = bx * 8 + wave, NGW = G * 8;
;         constexpr int I_IN = (DM / 64) * (9248 / 32), I_OUT = (DMIX / 64) * (DM / 32), I_UP = (DM / 64) * (FF2 / 32), I_DN = (FF / 64) * (DM / 32);
;         constexpr int n_items0 = I_IN + I_OUT + I_UP + I_DN;
;         for (int it = gw; it < n_items0; it += NGW) {
;             int r = it;
;             if (r < I_IN) { const int nblk = 9248 / 32, kb = r / nblk, nb = r % nblk; p0_transpose_item(w_in, DM, 9248, WinT, 64 * kb, 32 * nb, win_dest_row(32 * nb), scr, lane); continue; } r -= I_IN;
.LBB0_153:
	v_writelane_b32 v254, s3, 0
	v_writelane_b32 v254, s4, 1
	v_writelane_b32 v254, s8, 2
	v_writelane_b32 v254, s9, 3
	v_writelane_b32 v254, s10, 4
	v_writelane_b32 v254, s11, 5
	v_writelane_b32 v254, s12, 6
	v_writelane_b32 v254, s13, 7
	v_writelane_b32 v254, s14, 8
	v_writelane_b32 v254, s15, 9
	v_writelane_b32 v254, s16, 10
	v_writelane_b32 v254, s17, 11
	v_writelane_b32 v254, s18, 12
	v_writelane_b32 v254, s19, 13
	v_writelane_b32 v254, s20, 14
	v_writelane_b32 v254, s21, 15
	v_writelane_b32 v254, s22, 16
	v_writelane_b32 v254, s23, 17
	v_writelane_b32 v254, s24, 18
	v_writelane_b32 v254, s25, 19
	v_writelane_b32 v254, s26, 20
	v_writelane_b32 v254, s27, 21
	v_writelane_b32 v254, s28, 22
	v_writelane_b32 v254, s29, 23
	v_writelane_b32 v254, s30, 24
	v_writelane_b32 v254, s31, 25
	v_writelane_b32 v254, s32, 26
	v_writelane_b32 v254, s33, 27
	v_writelane_b32 v254, s34, 28
	v_writelane_b32 v254, s35, 29
	v_writelane_b32 v254, s36, 30
	v_writelane_b32 v254, s37, 31
	v_writelane_b32 v254, s38, 32
	v_writelane_b32 v254, s39, 33
	v_writelane_b32 v254, s40, 34
	v_writelane_b32 v254, s41, 35
	v_writelane_b32 v254, s42, 36
	v_writelane_b32 v254, s43, 37
	v_writelane_b32 v254, s44, 38
	v_writelane_b32 v254, s45, 39
	v_writelane_b32 v254, s46, 40
	v_writelane_b32 v254, s47, 41
	v_writelane_b32 v254, s48, 42
	v_writelane_b32 v254, s49, 43
	v_writelane_b32 v254, s50, 44
	v_writelane_b32 v254, s51, 45
	v_writelane_b32 v254, s52, 46
	v_writelane_b32 v254, s53, 47
	v_writelane_b32 v254, s54, 48
	v_writelane_b32 v254, s55, 49
	s_cmpk_lt_u32 s2, 234
	s_cbranch_scc1 .Ltup1_skip
	s_mov_b64 s[8:9], s[96:97]
	v_and_b32_e32 v3, 63, v212
	v_readfirstlane_b32 s4, v212
	s_sub_u32 s3, s2, 234
	s_lshl_b32 s3, s3, 3
	s_lshr_b32 s4, s4, 6
	s_add_u32 s3, s3, s4
	s_add_u32 s11, s3, 17456
	s_sub_u32 s10, s94, 234
	s_lshl_b32 s10, s10, 3
	s_cmpk_lt_u32 s11, 20256
	s_cbranch_scc0 .Ltup1_skip
	s_load_dwordx2 s[12:13], s[8:9], 0x38
	s_load_dwordx2 s[14:15], s[8:9], 0x90
	s_load_dwordx2 s[16:17], s[8:9], 0xa0
	s_load_dwordx2 s[18:19], s[8:9], 0xb8
	s_load_dwordx2 s[20:21], s[8:9], 0x98
	s_load_dwordx2 s[22:23], s[8:9], 0xd0
	v_lshrrev_b32_e32 v4, 3, v3
	v_and_b32_e32 v7, 7, v3
	v_lshlrev_b32_e32 v5, 4, v7
	v_lshlrev_b32_e32 v6, 5, v7
	s_lshl_b32 s24, s4, 14
	v_lshl_add_u32 v16, v4, 7, s24
	v_xor_b32_e32 v8, 0, v7
	v_lshl_add_u32 v8, v8, 4, v16
	v_xor_b32_e32 v9, 1, v7
	v_lshl_add_u32 v9, v9, 4, v16
	v_xor_b32_e32 v10, 2, v7
	v_lshl_add_u32 v10, v10, 4, v16
	v_xor_b32_e32 v11, 3, v7
	v_lshl_add_u32 v11, v11, 4, v16
	v_xor_b32_e32 v12, 4, v7
	v_lshl_add_u32 v12, v12, 4, v16
	v_xor_b32_e32 v13, 5, v7
	v_lshl_add_u32 v13, v13, 4, v16
	v_xor_b32_e32 v14, 6, v7
	v_lshl_add_u32 v14, v14, 4, v16
	v_xor_b32_e32 v15, 7, v7
	v_lshl_add_u32 v15, v15, 4, v16
	v_lshlrev_b32_e32 v20, 2, v7
	v_lshl_add_u32 v21, v7, 10, s24
	v_add_u32_e32 v16, 0, v4
	v_xor_b32_e32 v16, v16, v20
	v_lshl_add_u32 v16, v16, 2, v21
	v_add_u32_e32 v17, 8, v4
	v_xor_b32_e32 v17, v17, v20
	v_lshl_add_u32 v17, v17, 2, v21
	v_add_u32_e32 v18, 16, v4
	v_xor_b32_e32 v18, v18, v20
	v_lshl_add_u32 v18, v18, 2, v21
	v_add_u32_e32 v19, 24, v4
	v_xor_b32_e32 v19, v19, v20
	v_lshl_add_u32 v19, v19, 2, v21
	s_waitcnt lgkmcnt(0)
	s_cmpk_lt_u32 s11, 9248
	s_cbranch_scc0 .Ltup1_pro_notin
	s_mul_hi_u32 s40, s11, 14861479
	s_mul_i32 s42, s40, 289
	s_sub_u32 s41, s11, s42
	s_mul_i32 s42, s40, 2367488
	s_lshl_b32 s43, s41, 7
	s_add_u32 s42, s42, s43
	s_add_u32 s26, s12, s42
	s_addc_u32 s27, s13, 0
	s_mov_b32 s28, 36992
	s_lshl_b32 s45, s41, 5
	s_mov_b32 s46, s45
	s_cmpk_lt_u32 s45, 5120
	s_cbranch_scc1 .Ltup1_pro_drow_done
	s_movk_i32 s46, 9216
	s_cmpk_lt_u32 s45, 5152
	s_cbranch_scc1 .Ltup1_pro_drow_done
	s_sub_u32 s47, s45, 5152
	s_movk_i32 s43, 5120
	s_cmpk_lt_u32 s45, 7200
	s_cbranch_scc1 .Ltup1_pro_drow_cf
	s_sub_u32 s47, s45, 7200
	s_movk_i32 s43, 5248

; #define LAS __attribute__((address_space(3)))
; __device__ __forceinline__ int ltid() { int t = threadIdx.x; asm volatile("" : "+v"(t)); return t; }
; __device__ __forceinline__ KArgs ka_get() { KArgs p = (KArgs)__builtin_amdgcn_kernarg_segment_ptr(); asm volatile("" : "+s"(p)); return p; }
; __global__ void __launch_bounds__(512, 2) mk_fwd(Args args) {
;     ...
;     if (IN(0)) { const KArgs KA = ka_get(); const int tid = ltid(), lane = tid & 63, wave = __builtin_amdgcn_readfirstlane(tid >> 6); (void)lane; (void)wave;
;         LAS float* scr = (LAS float*)(lds + wave * 16384);
;         const int gw = bx * 8 + wave, NGW = G * 8;
;         constexpr int I_IN = (DM / 64) * (9248 / 32), I_OUT = (DMIX / 64) * (DM / 32), I_UP = (DM / 64) * (FF2 / 32), I_DN = (FF / 64) * (DM / 32);
;         constexpr int n_items0 = I_IN + I_OUT + I_UP + I_DN;
;         for (int it = gw; it < n_items0; it += NGW) {
;             int r = it;
;             if (r < I_IN) { const int nblk = 9248 / 32, kb = r / nblk, nb = r % nblk; p0_transpose_item(w_in, DM, 9248, WinT, 64 * kb, 32 * nb, win_dest_row(32 * nb), scr, lane); continue; } r -= I_IN;
.LBB0_491:
	v_writelane_b32 v254, s3, 0
	v_writelane_b32 v254, s4, 1
	v_writelane_b32 v254, s8, 2
	v_writelane_b32 v254, s9, 3
	v_writelane_b32 v254, s10, 4
	v_writelane_b32 v254, s11, 5
	v_writelane_b32 v254, s12, 6
	v_writelane_b32 v254, s13, 7
	v_writelane_b32 v254, s14, 8
	v_writelane_b32 v254, s15, 9
	v_writelane_b32 v254, s16, 10
	v_writelane_b32 v254, s17, 11
	v_writelane_b32 v254, s18, 12
	v_writelane_b32 v254, s19, 13
	v_writelane_b32 v254, s20, 14
	v_writelane_b32 v254, s21, 15
	v_writelane_b32 v254, s22, 16
	v_writelane_b32 v254, s23, 17
	v_writelane_b32 v254, s24, 18
	v_writelane_b32 v254, s25, 19
	v_writelane_b32 v254, s26, 20
	v_writelane_b32 v254, s27, 21
	v_writelane_b32 v254, s28, 22
	v_writelane_b32 v254, s29, 23
	v_writelane_b32 v254, s30, 24
	v_writelane_b32 v254, s31, 25
	v_writelane_b32 v254, s32, 26
	v_writelane_b32 v254, s33, 27
	v_writelane_b32 v254, s34, 28
	v_writelane_b32 v254, s35, 29
	v_writelane_b32 v254, s36, 30
	v_writelane_b32 v254, s37, 31
	v_writelane_b32 v254, s38, 32
	v_writelane_b32 v254, s39, 33
	v_writelane_b32 v254, s40, 34
	v_writelane_b32 v254, s41, 35
	v_writelane_b32 v254, s42, 36
	v_writelane_b32 v254, s43, 37
	v_writelane_b32 v254, s44, 38
	v_writelane_b32 v254, s45, 39
	v_writelane_b32 v254, s46, 40
	v_writelane_b32 v254, s47, 41
	v_writelane_b32 v254, s48, 42
	v_writelane_b32 v254, s49, 43
	v_writelane_b32 v254, s50, 44
	v_writelane_b32 v254, s51, 45
	v_writelane_b32 v254, s52, 46
	v_writelane_b32 v254, s53, 47
	v_writelane_b32 v254, s54, 48
	v_writelane_b32 v254, s55, 49
	s_cmpk_lt_u32 s2, 128
	s_cbranch_scc1 .Ltup3_skip
	s_mov_b64 s[8:9], s[96:97]
	v_and_b32_e32 v3, 63, v212
	v_readfirstlane_b32 s4, v212
	s_sub_u32 s3, s2, 128
	s_lshl_b32 s3, s3, 3
	s_lshr_b32 s4, s4, 6
	s_add_u32 s3, s3, s4
	s_add_u32 s11, s3, 14384
	s_sub_u32 s10, s94, 128
	s_lshl_b32 s10, s10, 3
	s_cmpk_lt_u32 s11, 17456
	s_cbranch_scc0 .Ltup3_skip
	s_load_dwordx2 s[12:13], s[8:9], 0x38
	s_load_dwordx2 s[14:15], s[8:9], 0x90
	s_load_dwordx2 s[16:17], s[8:9], 0xa0
	s_load_dwordx2 s[18:19], s[8:9], 0xb8
	s_load_dwordx2 s[20:21], s[8:9], 0x98
	s_load_dwordx2 s[22:23], s[8:9], 0xd0
	v_lshrrev_b32_e32 v4, 3, v3
	v_and_b32_e32 v7, 7, v3
	v_lshlrev_b32_e32 v5, 4, v7
	v_lshlrev_b32_e32 v6, 5, v7
	s_lshl_b32 s24, s4, 14
	v_lshl_add_u32 v16, v4, 7, s24
	v_xor_b32_e32 v8, 0, v7
	v_lshl_add_u32 v8, v8, 4, v16
	v_xor_b32_e32 v9, 1, v7
	v_lshl_add_u32 v9, v9, 4, v16
	v_xor_b32_e32 v10, 2, v7
	v_lshl_add_u32 v10, v10, 4, v16
	v_xor_b32_e32 v11, 3, v7
	v_lshl_add_u32 v11, v11, 4, v16
	v_xor_b32_e32 v12, 4, v7
	v_lshl_add_u32 v12, v12, 4, v16
	v_xor_b32_e32 v13, 5, v7
	v_lshl_add_u32 v13, v13, 4, v16
	v_xor_b32_e32 v14, 6, v7
	v_lshl_add_u32 v14, v14, 4, v16
	v_xor_b32_e32 v15, 7, v7
	v_lshl_add_u32 v15, v15, 4, v16
	v_lshlrev_b32_e32 v20, 2, v7
	v_lshl_add_u32 v21, v7, 10, s24
	v_add_u32_e32 v16, 0, v4
	v_xor_b32_e32 v16, v16, v20
	v_lshl_add_u32 v16, v16, 2, v21
	v_add_u32_e32 v17, 8, v4
	v_xor_b32_e32 v17, v17, v20
	v_lshl_add_u32 v17, v17, 2, v21
	v_add_u32_e32 v18, 16, v4
	v_xor_b32_e32 v18, v18, v20
	v_lshl_add_u32 v18, v18, 2, v21
	v_add_u32_e32 v19, 24, v4
	v_xor_b32_e32 v19, v19, v20
	v_lshl_add_u32 v19, v19, 2, v21
	s_waitcnt lgkmcnt(0)
	s_cmpk_lt_u32 s11, 9248
	s_cbranch_scc0 .Ltup3_pro_notin
	s_mul_hi_u32 s40, s11, 14861479
	s_mul_i32 s42, s40, 289
	s_sub_u32 s41, s11, s42
	s_mul_i32 s42, s40, 2367488
	s_lshl_b32 s43, s41, 7
	s_add_u32 s42, s42, s43
	s_add_u32 s26, s12, s42
	s_addc_u32 s27, s13, 0
	s_mov_b32 s28, 36992
	s_lshl_b32 s45, s41, 5
	s_mov_b32 s46, s45
	s_cmpk_lt_u32 s45, 5120
	s_cbranch_scc1 .Ltup3_pro_drow_done
	s_movk_i32 s46, 9216
	s_cmpk_lt_u32 s45, 5152
	s_cbranch_scc1 .Ltup3_pro_drow_done
	s_sub_u32 s47, s45, 5152
	s_movk_i32 s43, 5120
	s_cmpk_lt_u32 s45, 7200
	s_cbranch_scc1 .Ltup3_pro_drow_cf
	s_sub_u32 s47, s45, 7200
	s_movk_i32 s43, 5248

;     __host__ __device__ __forceinline__ unsigned long long nextp(int i) const { Unit u; if (!next(i, u)) return 0ull; return pack_unit(u); }
; #define PG8_STAGE(bufoff, gbase, voff) do { _Pragma("unroll") for (int _i = 0; _i < 2; ++_i) \
;         __builtin_amdgcn_global_load_lds((const unsigned*)((const char*)(gbase) + (voff)[_i]), (PG8_LAS unsigned*)(lds + (bufoff) + ldsw + _i * 8192), 16, 0, 0); } while (0)
; #define PG8_LDA(dst, b, h) do { _Pragma("unroll") for (int m = 0; m < 4; ++m) _Pragma("unroll") for (int k = 0; k < 2; ++k) dst[m][k] = *(const PG8_LAS bf16x8*)(lds + PG8_SA(b, h) + aoff + m * 2048 + k * 1024); } while (0)
; #define PG8_LDB(dst, b, h) do { _Pragma("unroll") for (int n = 0; n < 2; ++n) _Pragma("unroll") for (int k = 0; k < 2; ++k) dst[n][k] = *(const PG8_LAS bf16x8*)(lds + PG8_SB(b, h) + boff + n * 2048 + k * 1024); } while (0)
; #define PG8_WAIT_V(n) asm volatile("s_waitcnt vmcnt(" #n ")" ::: "memory")
; template <class Epi, class Sched, bool ALIGN_EPI = false, bool SP2 = false>
; __device__ __forceinline__ void gemm_phase(PG8_LAS unsigned char* lds, const Gemm g, const Sched& S, const Epi& E) {
;     ...
;         nxt = S.nextp(ui + 1); const bool has_next = (nxt != 0ull);
;         const char* nA = has_next ? (const char*)g.A + (size_t)UP_PM(nxt) * tstep + (size_t)UP_KT0(nxt) * kstep : cA; const char* nB = has_next ? (const char*)g.Bt + (size_t)UP_PN(nxt) * tstep + (size_t)UP_KT0(nxt) * kstep : cB;
;         const int nt = UP_NKT(cur);
;         for (int t = 0; t < nt; t += 2) {
;             const bool last = (t == nt - 2);
;             const char* a1 = cA + (size_t)(t + 1) * kstep;
;             const char* a2 = last ? nA : cA + (size_t)(t + 2) * kstep; const char* b2 = last ? nB : cB + (size_t)(t + 2) * kstep;
;             const char* a3 = a2 + kstep; const char* b3 = b2 + kstep;
;             if constexpr (SP2) {
;             PG8_LDB(B0, 0, 0); PG8_LDB(B1, 0, 1); PG8_SCHED; PG8_LDA(At, 0, 0); PG8_STAGE(PG8_SA(1, 1), a1 + hstep, voffA);
;             PG8_WAIT_V(8); PG8_WAIT_L(0); PG8_BAR; PG8_MMA(0, 0, At, B0); PG8_MMA(0, 1, At, B1); PG8_BAR; PG8_SCHED;
;             PG8_LDA(At, 0, 1); PG8_STAGE(PG8_SB(0, 0), b2, voffB); PG8_STAGE(PG8_SB(0, 1), b2 + hstep, voffB); PG8_STAGE(PG8_SA(0, 0), a2, voffA);
;             PG8_WAIT_V(8); PG8_WAIT_L(0); PG8_BAR; PG8_MMA(1, 0, At, B0); PG8_MMA(1, 1, At, B1); PG8_BAR; PG8_SCHED;
.LBB0_647:
	ds_read_b128 v[128:131], v185
	ds_read_b128 v[132:135], v185 offset:1024
	ds_read_b128 v[136:139], v185 offset:2048
	ds_read_b128 v[140:143], v185 offset:3072
	ds_read_b128 v[144:147], v186
	ds_read_b128 v[148:151], v186 offset:1024
	ds_read_b128 v[152:155], v186 offset:2048
	ds_read_b128 v[156:159], v186 offset:3072
	s_add_i32 s84, s56, 2
	s_add_u32 s57, s54, 0xfff00080
	s_addc_u32 s58, s55, -1
	s_cmp_eq_u32 s81, s56
	s_cselect_b32 s56, s50, s82
	s_cselect_b32 s59, s49, s58
	s_cselect_b32 s58, s48, s57
	s_cselect_b32 s57, s51, s83
	v_lshl_add_u64 v[180:181], s[54:55], 0, v[170:171]
	s_add_i32 m0, s63, 0xc000
	ds_read_b128 v[176:179], v187
	ds_read_b128 v[190:193], v187 offset:1024
	ds_read_b128 v[194:197], v187 offset:2048
	ds_read_b128 v[198:201], v187 offset:3072
	ds_read_b128 v[202:205], v187 offset:4096
	ds_read_b128 v[206:209], v187 offset:5120
	ds_read_b128 v[214:217], v187 offset:6144
	ds_read_b128 v[218:221], v187 offset:7168
	global_load_lds_dwordx4 v[180:181], off
	v_lshl_add_u64 v[180:181], s[54:55], 0, v[172:173]
	s_add_i32 m0, s63, 0xe000
	s_nop 0
	global_load_lds_dwordx4 v[180:181], off
	s_waitcnt vmcnt(8)
	s_waitcnt lgkmcnt(0)
	s_barrier
	s_setprio 1
	s_waitcnt lgkmcnt(0)
	v_mfma_f32_16x16x32_bf16 v[124:127], v[128:131], v[176:179], v[124:127]
	v_mfma_f32_16x16x32_bf16 v[120:123], v[136:139], v[176:179], v[120:123]
	v_mfma_f32_16x16x32_bf16 v[108:111], v[128:131], v[194:197], v[108:111]
	v_mfma_f32_16x16x32_bf16 v[104:107], v[136:139], v[194:197], v[104:107]
	v_mfma_f32_16x16x32_bf16 v[92:95], v[128:131], v[202:205], v[92:95]
	v_mfma_f32_16x16x32_bf16 v[88:91], v[136:139], v[202:205], v[88:91]
	v_mfma_f32_16x16x32_bf16 v[76:79], v[128:131], v[214:217], v[76:79]
	v_mfma_f32_16x16x32_bf16 v[72:75], v[136:139], v[214:217], v[72:75]
	v_mfma_f32_16x16x32_bf16 v[124:127], v[132:135], v[190:193], v[124:127]
	v_mfma_f32_16x16x32_bf16 v[120:123], v[140:143], v[190:193], v[120:123]
	v_mfma_f32_16x16x32_bf16 v[108:111], v[132:135], v[198:201], v[108:111]
	v_mfma_f32_16x16x32_bf16 v[104:107], v[140:143], v[198:201], v[104:107]
	v_mfma_f32_16x16x32_bf16 v[92:95], v[132:135], v[206:209], v[92:95]
	v_mfma_f32_16x16x32_bf16 v[88:91], v[140:143], v[206:209], v[88:91]
	v_mfma_f32_16x16x32_bf16 v[76:79], v[132:135], v[218:221], v[76:79]
	v_mfma_f32_16x16x32_bf16 v[72:75], v[140:143], v[218:221], v[72:75]
	s_setprio 0
	s_setprio 1
	v_mfma_f32_16x16x32_bf16 v[116:119], v[144:147], v[176:179], v[116:119]
	v_mfma_f32_16x16x32_bf16 v[112:115], v[152:155], v[176:179], v[112:115]
	v_mfma_f32_16x16x32_bf16 v[100:103], v[144:147], v[194:197], v[100:103]
	v_mfma_f32_16x16x32_bf16 v[96:99], v[152:155], v[194:197], v[96:99]
	v_mfma_f32_16x16x32_bf16 v[84:87], v[144:147], v[202:205], v[84:87]
	v_mfma_f32_16x16x32_bf16 v[80:83], v[152:155], v[202:205], v[80:83]
	v_mfma_f32_16x16x32_bf16 v[68:71], v[144:147], v[214:217], v[68:71]
	v_mfma_f32_16x16x32_bf16 v[64:67], v[152:155], v[214:217], v[64:67]
	v_mfma_f32_16x16x32_bf16 v[116:119], v[148:151], v[190:193], v[116:119]
	v_mfma_f32_16x16x32_bf16 v[112:115], v[156:159], v[190:193], v[112:115]
	v_mfma_f32_16x16x32_bf16 v[100:103], v[148:151], v[198:201], v[100:103]
	v_mfma_f32_16x16x32_bf16 v[96:99], v[156:159], v[198:201], v[96:99]
	v_mfma_f32_16x16x32_bf16 v[84:87], v[148:151], v[206:209], v[84:87]
	v_mfma_f32_16x16x32_bf16 v[80:83], v[156:159], v[206:209], v[80:83]
	v_mfma_f32_16x16x32_bf16 v[68:71], v[148:151], v[218:221], v[68:71]
	v_mfma_f32_16x16x32_bf16 v[64:67], v[156:159], v[218:221], v[64:67]
	s_setprio 0
	s_barrier
	s_add_i32 s85, s73, s62
	v_lshl_add_u64 v[180:181], s[56:57], 0, v[162:163]
	s_mov_b32 m0, s85
	ds_read_b128 v[176:179], v187 offset:16384
	ds_read_b128 v[190:193], v187 offset:17408
	ds_read_b128 v[194:197], v187 offset:18432
	ds_read_b128 v[198:201], v187 offset:19456
	ds_read_b128 v[202:205], v187 offset:20480
	ds_read_b128 v[206:209], v187 offset:21504
	ds_read_b128 v[214:217], v187 offset:22528
	ds_read_b128 v[218:221], v187 offset:23552
	global_load_lds_dwordx4 v[180:181], off
	s_add_i32 m0, s85, 0x2000
	s_add_u32 s86, s56, 0x100000
	v_lshl_add_u64 v[210:211], s[56:57], 0, v[166:167]
	s_addc_u32 s87, s57, 0
	s_add_i32 s85, s74, s62
	global_load_lds_dwordx4 v[210:211], off
	v_lshl_add_u64 v[222:223], s[86:87], 0, v[162:163]
	s_mov_b32 m0, s85
	v_lshl_add_u64 v[224:225], s[58:59], 0, v[164:165]
	global_load_lds_dwordx4 v[222:223], off
	v_lshl_add_u64 v[222:223], s[86:87], 0, v[166:167]
	s_add_i32 m0, s85, 0x2000
	s_nop 0
	global_load_lds_dwordx4 v[222:223], off
	v_lshl_add_u64 v[222:223], s[58:59], 0, v[160:161]
	s_mov_b32 m0, s63
	s_nop 0
	global_load_lds_dwordx4 v[222:223], off
	s_mov_b32 m0, s64
	s_nop 0
	global_load_lds_dwordx4 v[224:225], off
	s_waitcnt vmcnt(8)
	s_waitcnt lgkmcnt(0)
	s_barrier
; #define PG8_STAGE(bufoff, gbase, voff) do { _Pragma("unroll") for (int _i = 0; _i < 2; ++_i) \
;         __builtin_amdgcn_global_load_lds((const unsigned*)((const char*)(gbase) + (voff)[_i]), (PG8_LAS unsigned*)(lds + (bufoff) + ldsw + _i * 8192), 16, 0, 0); } while (0)
; #define PG8_LDA(dst, b, h) do { _Pragma("unroll") for (int m = 0; m < 4; ++m) _Pragma("unroll") for (int k = 0; k < 2; ++k) dst[m][k] = *(const PG8_LAS bf16x8*)(lds + PG8_SA(b, h) + aoff + m * 2048 + k * 1024); } while (0)
; #define PG8_LDB(dst, b, h) do { _Pragma("unroll") for (int n = 0; n < 2; ++n) _Pragma("unroll") for (int k = 0; k < 2; ++k) dst[n][k] = *(const PG8_LAS bf16x8*)(lds + PG8_SB(b, h) + boff + n * 2048 + k * 1024); } while (0)
; #define PG8_MMA(ai, bj, At, Bt) do { __builtin_amdgcn_s_setprio(1); _Pragma("unroll") for (int m = 0; m < 4; ++m) _Pragma("unroll") for (int n = 0; n < 2; ++n) _Pragma("unroll") for (int k = 0; k < 2; ++k) \
;         acc[ai][bj][m][n] = __builtin_amdgcn_mfma_f32_16x16x32_bf16(Bt[n][k], At[m][k], acc[ai][bj][m][n], 0, 0, 0); __builtin_amdgcn_s_setprio(0); } while (0)
; #define PG8_WAIT_V(n) asm volatile("s_waitcnt vmcnt(" #n ")" ::: "memory")
; #define PG8_WAIT_L(n) asm volatile("s_waitcnt lgkmcnt(" #n ")" ::: "memory")
; #define PG8_BAR __builtin_amdgcn_s_barrier()
; #define PG8_SCHED __builtin_amdgcn_sched_barrier(0)
; template <class Epi, class Sched, bool ALIGN_EPI = false, bool SP2 = false>
; __device__ __forceinline__ void gemm_phase(PG8_LAS unsigned char* lds, const Gemm g, const Sched& S, const Epi& E) {
;     ...
;             PG8_WAIT_V(8); PG8_WAIT_L(0); PG8_BAR; PG8_MMA(1, 0, At, B0); PG8_MMA(1, 1, At, B1); PG8_BAR; PG8_SCHED;
;             PG8_LDB(B0, 1, 0); PG8_LDB(B1, 1, 1); PG8_SCHED; PG8_LDA(At, 1, 0); PG8_STAGE(PG8_SA(0, 1), a2 + hstep, voffA);
;             PG8_WAIT_V(8); PG8_WAIT_L(0); PG8_BAR; PG8_MMA(0, 0, At, B0); PG8_MMA(0, 1, At, B1); PG8_BAR; PG8_SCHED;
	s_setprio 1
	s_waitcnt lgkmcnt(0)
	v_mfma_f32_16x16x32_bf16 v[60:63], v[128:131], v[176:179], v[60:63]
	v_mfma_f32_16x16x32_bf16 v[56:59], v[136:139], v[176:179], v[56:59]
	v_mfma_f32_16x16x32_bf16 v[44:47], v[128:131], v[194:197], v[44:47]
	v_mfma_f32_16x16x32_bf16 v[40:43], v[136:139], v[194:197], v[40:43]
	v_mfma_f32_16x16x32_bf16 v[28:31], v[128:131], v[202:205], v[28:31]
	v_mfma_f32_16x16x32_bf16 v[24:27], v[136:139], v[202:205], v[24:27]
	v_mfma_f32_16x16x32_bf16 v[12:15], v[128:131], v[214:217], v[12:15]
	v_mfma_f32_16x16x32_bf16 v[8:11], v[136:139], v[214:217], v[8:11]
	v_mfma_f32_16x16x32_bf16 v[60:63], v[132:135], v[190:193], v[60:63]
	v_mfma_f32_16x16x32_bf16 v[56:59], v[140:143], v[190:193], v[56:59]
	v_mfma_f32_16x16x32_bf16 v[44:47], v[132:135], v[198:201], v[44:47]
	v_mfma_f32_16x16x32_bf16 v[40:43], v[140:143], v[198:201], v[40:43]
	v_mfma_f32_16x16x32_bf16 v[28:31], v[132:135], v[206:209], v[28:31]
	v_mfma_f32_16x16x32_bf16 v[24:27], v[140:143], v[206:209], v[24:27]
	v_mfma_f32_16x16x32_bf16 v[12:15], v[132:135], v[218:221], v[12:15]
	v_mfma_f32_16x16x32_bf16 v[8:11], v[140:143], v[218:221], v[8:11]
	s_setprio 0
	s_setprio 1
	v_mfma_f32_16x16x32_bf16 v[52:55], v[144:147], v[176:179], v[52:55]
	v_mfma_f32_16x16x32_bf16 v[48:51], v[152:155], v[176:179], v[48:51]
	v_mfma_f32_16x16x32_bf16 v[36:39], v[144:147], v[194:197], v[36:39]
	v_mfma_f32_16x16x32_bf16 v[32:35], v[152:155], v[194:197], v[32:35]
	v_mfma_f32_16x16x32_bf16 v[20:23], v[144:147], v[202:205], v[20:23]
	v_mfma_f32_16x16x32_bf16 v[16:19], v[152:155], v[202:205], v[16:19]
	v_mfma_f32_16x16x32_bf16 v[4:7], v[144:147], v[214:217], v[4:7]
	v_mfma_f32_16x16x32_bf16 v[0:3], v[152:155], v[214:217], v[0:3]
	v_mfma_f32_16x16x32_bf16 v[52:55], v[148:151], v[190:193], v[52:55]
	v_mfma_f32_16x16x32_bf16 v[48:51], v[156:159], v[190:193], v[48:51]
	v_mfma_f32_16x16x32_bf16 v[36:39], v[148:151], v[198:201], v[36:39]
	v_mfma_f32_16x16x32_bf16 v[32:35], v[156:159], v[198:201], v[32:35]
	v_mfma_f32_16x16x32_bf16 v[20:23], v[148:151], v[206:209], v[20:23]
	v_mfma_f32_16x16x32_bf16 v[16:19], v[156:159], v[206:209], v[16:19]
	v_mfma_f32_16x16x32_bf16 v[4:7], v[148:151], v[218:221], v[4:7]
	v_mfma_f32_16x16x32_bf16 v[0:3], v[156:159], v[218:221], v[0:3]
	s_setprio 0
	s_barrier
	s_add_i32 s85, 0, 0x18000
	s_add_i32 s86, 0, 0x1c000
	v_add_u32_e32 v140, s85, v183
	v_add_u32_e32 v156, s86, v183
	ds_read_b128 v[128:131], v140
	ds_read_b128 v[132:135], v140 offset:1024
	ds_read_b128 v[136:139], v140 offset:2048
	ds_read_b128 v[140:143], v140 offset:3072
	ds_read_b128 v[144:147], v156
	ds_read_b128 v[148:151], v156 offset:1024
	ds_read_b128 v[152:155], v156 offset:2048
	ds_read_b128 v[156:159], v156 offset:3072
	s_add_u32 s58, s58, 0x100000
	s_addc_u32 s59, s59, 0
	s_mov_b32 m0, s65
	v_lshl_add_u64 v[226:227], s[58:59], 0, v[160:161]
	ds_read_b128 v[176:179], v187 offset:32768
	ds_read_b128 v[190:193], v187 offset:33792
	ds_read_b128 v[194:197], v187 offset:34816
	ds_read_b128 v[198:201], v187 offset:35840
	ds_read_b128 v[202:205], v187 offset:36864
	ds_read_b128 v[206:209], v187 offset:37888
	ds_read_b128 v[214:217], v187 offset:38912
	ds_read_b128 v[218:221], v187 offset:39936
	global_load_lds_dwordx4 v[226:227], off
	v_lshl_add_u64 v[226:227], s[58:59], 0, v[164:165]
	s_mov_b32 m0, s66
	s_nop 0
	global_load_lds_dwordx4 v[226:227], off
	s_waitcnt vmcnt(8)
	s_waitcnt lgkmcnt(0)
	s_barrier
	s_setprio 1
	s_waitcnt lgkmcnt(0)
	v_mfma_f32_16x16x32_bf16 v[124:127], v[128:131], v[176:179], v[124:127]
	v_mfma_f32_16x16x32_bf16 v[120:123], v[136:139], v[176:179], v[120:123]
	v_mfma_f32_16x16x32_bf16 v[108:111], v[128:131], v[194:197], v[108:111]
	v_mfma_f32_16x16x32_bf16 v[104:107], v[136:139], v[194:197], v[104:107]
	v_mfma_f32_16x16x32_bf16 v[92:95], v[128:131], v[202:205], v[92:95]
	v_mfma_f32_16x16x32_bf16 v[88:91], v[136:139], v[202:205], v[88:91]
	v_mfma_f32_16x16x32_bf16 v[76:79], v[128:131], v[214:217], v[76:79]
	v_mfma_f32_16x16x32_bf16 v[72:75], v[136:139], v[214:217], v[72:75]
	v_mfma_f32_16x16x32_bf16 v[124:127], v[132:135], v[190:193], v[124:127]
	v_mfma_f32_16x16x32_bf16 v[120:123], v[140:143], v[190:193], v[120:123]
	v_mfma_f32_16x16x32_bf16 v[108:111], v[132:135], v[198:201], v[108:111]
	v_mfma_f32_16x16x32_bf16 v[104:107], v[140:143], v[198:201], v[104:107]
	v_mfma_f32_16x16x32_bf16 v[92:95], v[132:135], v[206:209], v[92:95]
	v_mfma_f32_16x16x32_bf16 v[88:91], v[140:143], v[206:209], v[88:91]
	v_mfma_f32_16x16x32_bf16 v[76:79], v[132:135], v[218:221], v[76:79]
	v_mfma_f32_16x16x32_bf16 v[72:75], v[140:143], v[218:221], v[72:75]
	s_setprio 0
	s_setprio 1
	v_mfma_f32_16x16x32_bf16 v[116:119], v[144:147], v[176:179], v[116:119]
	v_mfma_f32_16x16x32_bf16 v[112:115], v[152:155], v[176:179], v[112:115]
	v_mfma_f32_16x16x32_bf16 v[100:103], v[144:147], v[194:197], v[100:103]
	v_mfma_f32_16x16x32_bf16 v[96:99], v[152:155], v[194:197], v[96:99]
	v_mfma_f32_16x16x32_bf16 v[84:87], v[144:147], v[202:205], v[84:87]
	v_mfma_f32_16x16x32_bf16 v[80:83], v[152:155], v[202:205], v[80:83]
	v_mfma_f32_16x16x32_bf16 v[68:71], v[144:147], v[214:217], v[68:71]
	v_mfma_f32_16x16x32_bf16 v[64:67], v[152:155], v[214:217], v[64:67]
	v_mfma_f32_16x16x32_bf16 v[116:119], v[148:151], v[190:193], v[116:119]
	v_mfma_f32_16x16x32_bf16 v[112:115], v[156:159], v[190:193], v[112:115]
	v_mfma_f32_16x16x32_bf16 v[100:103], v[148:151], v[198:201], v[100:103]
	v_mfma_f32_16x16x32_bf16 v[96:99], v[156:159], v[198:201], v[96:99]
	v_mfma_f32_16x16x32_bf16 v[84:87], v[148:151], v[206:209], v[84:87]
	v_mfma_f32_16x16x32_bf16 v[80:83], v[156:159], v[206:209], v[80:83]
	v_mfma_f32_16x16x32_bf16 v[68:71], v[148:151], v[218:221], v[68:71]
	v_mfma_f32_16x16x32_bf16 v[64:67], v[156:159], v[218:221], v[64:67]
	s_setprio 0
	s_barrier
; #define PG8_STAGE(bufoff, gbase, voff) do { _Pragma("unroll") for (int _i = 0; _i < 2; ++_i) \
;         __builtin_amdgcn_global_load_lds((const unsigned*)((const char*)(gbase) + (voff)[_i]), (PG8_LAS unsigned*)(lds + (bufoff) + ldsw + _i * 8192), 16, 0, 0); } while (0)
; #define PG8_LDA(dst, b, h) do { _Pragma("unroll") for (int m = 0; m < 4; ++m) _Pragma("unroll") for (int k = 0; k < 2; ++k) dst[m][k] = *(const PG8_LAS bf16x8*)(lds + PG8_SA(b, h) + aoff + m * 2048 + k * 1024); } while (0)
; #define PG8_MMA(ai, bj, At, Bt) do { __builtin_amdgcn_s_setprio(1); _Pragma("unroll") for (int m = 0; m < 4; ++m) _Pragma("unroll") for (int n = 0; n < 2; ++n) _Pragma("unroll") for (int k = 0; k < 2; ++k) \
;         acc[ai][bj][m][n] = __builtin_amdgcn_mfma_f32_16x16x32_bf16(Bt[n][k], At[m][k], acc[ai][bj][m][n], 0, 0, 0); __builtin_amdgcn_s_setprio(0); } while (0)
; #define PG8_WAIT_V(n) asm volatile("s_waitcnt vmcnt(" #n ")" ::: "memory")
; #define PG8_WAIT_L(n) asm volatile("s_waitcnt lgkmcnt(" #n ")" ::: "memory")
; #define PG8_BAR __builtin_amdgcn_s_barrier()
; #define PG8_SCHED __builtin_amdgcn_sched_barrier(0)
; template <class Epi, class Sched, bool ALIGN_EPI = false, bool SP2 = false>
; __device__ __forceinline__ void gemm_phase(PG8_LAS unsigned char* lds, const Gemm g, const Sched& S, const Epi& E) {
;     ...
;         for (int t = 0; t < nt; t += 2) {
;     ...
;             PG8_LDA(At, 1, 1); PG8_STAGE(PG8_SB(1, 0), b3, voffB); PG8_STAGE(PG8_SB(1, 1), b3 + hstep, voffB); PG8_STAGE(PG8_SA(1, 0), a3, voffA);
;             PG8_WAIT_V(8); PG8_WAIT_L(0); PG8_BAR; PG8_MMA(1, 0, At, B0); PG8_MMA(1, 1, At, B1); PG8_BAR; PG8_SCHED;
	s_add_i32 s58, s85, s62
	v_lshl_add_u64 v[180:181], v[180:181], 0, s[18:19]
	s_mov_b32 m0, s58
	ds_read_b128 v[176:179], v187 offset:49152
	ds_read_b128 v[190:193], v187 offset:50176
	ds_read_b128 v[194:197], v187 offset:51200
	ds_read_b128 v[198:201], v187 offset:52224
	ds_read_b128 v[202:205], v187 offset:53248
	ds_read_b128 v[206:209], v187 offset:54272
	ds_read_b128 v[214:217], v187 offset:55296
	ds_read_b128 v[218:221], v187 offset:56320
	global_load_lds_dwordx4 v[180:181], off
	s_add_i32 m0, s58, 0x2000
	s_add_u32 s56, s56, 0x100080
	v_lshl_add_u64 v[180:181], v[210:211], 0, s[18:19]
	s_addc_u32 s57, s57, 0
	s_add_i32 s58, s86, s62
	global_load_lds_dwordx4 v[180:181], off
	v_lshl_add_u64 v[180:181], s[56:57], 0, v[162:163]
	s_mov_b32 m0, s58
	s_nop 0
	global_load_lds_dwordx4 v[180:181], off
	v_lshl_add_u64 v[180:181], s[56:57], 0, v[166:167]
	s_add_i32 m0, s58, 0x2000
	s_nop 0
	global_load_lds_dwordx4 v[180:181], off
	v_lshl_add_u64 v[180:181], v[222:223], 0, s[18:19]
	s_mov_b32 m0, s69
	s_nop 0
	global_load_lds_dwordx4 v[180:181], off
	v_lshl_add_u64 v[180:181], v[224:225], 0, s[18:19]
	s_mov_b32 m0, s70
	s_nop 0
	global_load_lds_dwordx4 v[180:181], off
	s_waitcnt vmcnt(8)
	s_waitcnt lgkmcnt(0)
	s_barrier
	s_setprio 1
	s_waitcnt lgkmcnt(0)
	v_mfma_f32_16x16x32_bf16 v[60:63], v[128:131], v[176:179], v[60:63]
	v_mfma_f32_16x16x32_bf16 v[56:59], v[136:139], v[176:179], v[56:59]
	v_mfma_f32_16x16x32_bf16 v[44:47], v[128:131], v[194:197], v[44:47]
	v_mfma_f32_16x16x32_bf16 v[40:43], v[136:139], v[194:197], v[40:43]
	v_mfma_f32_16x16x32_bf16 v[28:31], v[128:131], v[202:205], v[28:31]
	v_mfma_f32_16x16x32_bf16 v[24:27], v[136:139], v[202:205], v[24:27]
	v_mfma_f32_16x16x32_bf16 v[12:15], v[128:131], v[214:217], v[12:15]
	v_mfma_f32_16x16x32_bf16 v[8:11], v[136:139], v[214:217], v[8:11]
	v_mfma_f32_16x16x32_bf16 v[60:63], v[132:135], v[190:193], v[60:63]
	v_mfma_f32_16x16x32_bf16 v[56:59], v[140:143], v[190:193], v[56:59]
	v_mfma_f32_16x16x32_bf16 v[44:47], v[132:135], v[198:201], v[44:47]
	v_mfma_f32_16x16x32_bf16 v[40:43], v[140:143], v[198:201], v[40:43]
	v_mfma_f32_16x16x32_bf16 v[28:31], v[132:135], v[206:209], v[28:31]
	v_mfma_f32_16x16x32_bf16 v[24:27], v[140:143], v[206:209], v[24:27]
	v_mfma_f32_16x16x32_bf16 v[12:15], v[132:135], v[218:221], v[12:15]
	v_mfma_f32_16x16x32_bf16 v[8:11], v[140:143], v[218:221], v[8:11]
	s_setprio 0
	s_setprio 1
	v_mfma_f32_16x16x32_bf16 v[52:55], v[144:147], v[176:179], v[52:55]
	v_mfma_f32_16x16x32_bf16 v[48:51], v[152:155], v[176:179], v[48:51]
	v_mfma_f32_16x16x32_bf16 v[36:39], v[144:147], v[194:197], v[36:39]
	v_mfma_f32_16x16x32_bf16 v[32:35], v[152:155], v[194:197], v[32:35]
	v_mfma_f32_16x16x32_bf16 v[20:23], v[144:147], v[202:205], v[20:23]
	v_mfma_f32_16x16x32_bf16 v[16:19], v[152:155], v[202:205], v[16:19]
	v_mfma_f32_16x16x32_bf16 v[4:7], v[144:147], v[214:217], v[4:7]
	v_mfma_f32_16x16x32_bf16 v[0:3], v[152:155], v[214:217], v[0:3]
	v_mfma_f32_16x16x32_bf16 v[52:55], v[148:151], v[190:193], v[52:55]
	v_mfma_f32_16x16x32_bf16 v[48:51], v[156:159], v[190:193], v[48:51]
	v_mfma_f32_16x16x32_bf16 v[36:39], v[148:151], v[198:201], v[36:39]
	v_mfma_f32_16x16x32_bf16 v[32:35], v[156:159], v[198:201], v[32:35]
	v_mfma_f32_16x16x32_bf16 v[20:23], v[148:151], v[206:209], v[20:23]
	v_mfma_f32_16x16x32_bf16 v[16:19], v[156:159], v[206:209], v[16:19]
	v_mfma_f32_16x16x32_bf16 v[4:7], v[148:151], v[218:221], v[4:7]
	v_mfma_f32_16x16x32_bf16 v[0:3], v[156:159], v[218:221], v[0:3]
	s_setprio 0
	s_add_u32 s54, s54, 0x100
	s_addc_u32 s55, s55, 0
	s_add_u32 s82, s82, 0x100
	s_addc_u32 s83, s83, 0
	s_cmp_ge_u32 s84, s11
	s_mov_b32 s56, s84
	s_barrier
	s_cbranch_scc0 .LBB0_647

; __device__ __forceinline__ int win_dest_row(int n0) {
;     if (n0 < 5120) return n0;
;     if (n0 < 5152) return CDT + (n0 - 5120);
;     if (n0 < 7200) { const int c = n0 - 5152; return CCF + 256 * (c >> 7) + (c & 127); }
;     { const int c = n0 - 7200; return CCF + 256 * (c >> 7) + 128 + (c & 127); }
; }
; __global__ void __launch_bounds__(512, 2) mk_fwd(Args args) {
;     ...
;         constexpr int I_IN = (DM / 64) * (9248 / 32), I_OUT = (DMIX / 64) * (DM / 32), I_UP = (DM / 64) * (FF2 / 32), I_DN = (FF / 64) * (DM / 32);
;         constexpr int n_items0 = I_IN + I_OUT + I_UP + I_DN;
;         for (int it = gw; it < n_items0; it += NGW) {
;             int r = it;
;             if (r < I_IN) { const int nblk = 9248 / 32, kb = r / nblk, nb = r % nblk; p0_transpose_item(w_in, DM, 9248, WinT, 64 * kb, 32 * nb, win_dest_row(32 * nb), scr, lane); continue; } r -= I_IN;
;             if (r < I_OUT) { const int nblk = DM / 32, kb = r / nblk, nb = r % nblk; p0_transpose_item(w_out, DMIX, DM, WoutT, 64 * kb, 32 * nb, 32 * nb, scr, lane); continue; } r -= I_OUT;
;             if (r < I_UP) { const int nblk = FF2 / 32, kb = r / nblk, nb = r % nblk; p0_transpose_item(w_up, DM, FF2, WupT, 64 * kb, 32 * nb, 32 * nb, scr, lane, norm_ffn_w); continue; } r -= I_UP;
;             { const int nblk = DM / 32, kb = r / nblk, nb = r % nblk; p0_transpose_item(w_down, FF, DM, WdnT, 64 * kb, 32 * nb, 32 * nb, scr, lane); }
.LBB0_675:
	v_writelane_b32 v254, s3, 0
	v_writelane_b32 v254, s4, 1
	v_writelane_b32 v254, s8, 2
	v_writelane_b32 v254, s9, 3
	v_writelane_b32 v254, s10, 4
	v_writelane_b32 v254, s11, 5
	v_writelane_b32 v254, s12, 6
	v_writelane_b32 v254, s13, 7
	v_writelane_b32 v254, s14, 8
	v_writelane_b32 v254, s15, 9
	v_writelane_b32 v254, s16, 10
	v_writelane_b32 v254, s17, 11
	v_writelane_b32 v254, s18, 12
	v_writelane_b32 v254, s19, 13
	v_writelane_b32 v254, s20, 14
	v_writelane_b32 v254, s21, 15
	v_writelane_b32 v254, s22, 16
	v_writelane_b32 v254, s23, 17
	v_writelane_b32 v254, s24, 18
	v_writelane_b32 v254, s25, 19
	v_writelane_b32 v254, s26, 20
	v_writelane_b32 v254, s27, 21
	v_writelane_b32 v254, s28, 22
	v_writelane_b32 v254, s29, 23
	v_writelane_b32 v254, s30, 24
	v_writelane_b32 v254, s31, 25
	v_writelane_b32 v254, s32, 26
	v_writelane_b32 v254, s33, 27
	v_writelane_b32 v254, s34, 28
	v_writelane_b32 v254, s35, 29
	v_writelane_b32 v254, s36, 30
	v_writelane_b32 v254, s37, 31
	v_writelane_b32 v254, s38, 32
	v_writelane_b32 v254, s39, 33
	v_writelane_b32 v254, s40, 34
	v_writelane_b32 v254, s41, 35
	v_writelane_b32 v254, s42, 36
	v_writelane_b32 v254, s43, 37
	v_writelane_b32 v254, s44, 38
	v_writelane_b32 v254, s45, 39
	v_writelane_b32 v254, s46, 40
	v_writelane_b32 v254, s47, 41
	v_writelane_b32 v254, s48, 42
	v_writelane_b32 v254, s49, 43
	v_writelane_b32 v254, s50, 44
	v_writelane_b32 v254, s51, 45
	v_writelane_b32 v254, s52, 46
	v_writelane_b32 v254, s53, 47
	v_writelane_b32 v254, s54, 48
	v_writelane_b32 v254, s55, 49
	s_cmpk_lt_u32 s2, 128
	s_cbranch_scc1 .Ltup2_skip
	s_mov_b64 s[8:9], s[96:97]
	v_and_b32_e32 v3, 63, v212
	v_readfirstlane_b32 s4, v212
	s_sub_u32 s3, s2, 128
	s_lshl_b32 s3, s3, 3
	s_lshr_b32 s4, s4, 6
	s_add_u32 s3, s3, s4
	s_add_u32 s11, s3, 20256
	s_sub_u32 s10, s94, 128
	s_lshl_b32 s10, s10, 3
	s_cmpk_lt_u32 s11, 24352
	s_cbranch_scc0 .Ltup2_skip
	s_load_dwordx2 s[12:13], s[8:9], 0x38
	s_load_dwordx2 s[14:15], s[8:9], 0x90
	s_load_dwordx2 s[16:17], s[8:9], 0xa0
	s_load_dwordx2 s[18:19], s[8:9], 0xb8
	s_load_dwordx2 s[20:21], s[8:9], 0x98
	s_load_dwordx2 s[22:23], s[8:9], 0xd0
	v_lshrrev_b32_e32 v4, 3, v3
	v_and_b32_e32 v7, 7, v3
	v_lshlrev_b32_e32 v5, 4, v7
	v_lshlrev_b32_e32 v6, 5, v7
	s_lshl_b32 s24, s4, 14
	v_lshl_add_u32 v16, v4, 7, s24
	v_xor_b32_e32 v8, 0, v7
	v_lshl_add_u32 v8, v8, 4, v16
	v_xor_b32_e32 v9, 1, v7
	v_lshl_add_u32 v9, v9, 4, v16
	v_xor_b32_e32 v10, 2, v7
	v_lshl_add_u32 v10, v10, 4, v16
	v_xor_b32_e32 v11, 3, v7
	v_lshl_add_u32 v11, v11, 4, v16
	v_xor_b32_e32 v12, 4, v7
	v_lshl_add_u32 v12, v12, 4, v16
	v_xor_b32_e32 v13, 5, v7
	v_lshl_add_u32 v13, v13, 4, v16
	v_xor_b32_e32 v14, 6, v7
	v_lshl_add_u32 v14, v14, 4, v16
	v_xor_b32_e32 v15, 7, v7
	v_lshl_add_u32 v15, v15, 4, v16
	v_lshlrev_b32_e32 v20, 2, v7
	v_lshl_add_u32 v21, v7, 10, s24
	v_add_u32_e32 v16, 0, v4
	v_xor_b32_e32 v16, v16, v20
	v_lshl_add_u32 v16, v16, 2, v21
	v_add_u32_e32 v17, 8, v4
	v_xor_b32_e32 v17, v17, v20
	v_lshl_add_u32 v17, v17, 2, v21
	v_add_u32_e32 v18, 16, v4
	v_xor_b32_e32 v18, v18, v20
	v_lshl_add_u32 v18, v18, 2, v21
	v_add_u32_e32 v19, 24, v4
	v_xor_b32_e32 v19, v19, v20
	v_lshl_add_u32 v19, v19, 2, v21
	s_waitcnt lgkmcnt(0)
	s_cmpk_lt_u32 s11, 9248
	s_cbranch_scc0 .Ltup2_pro_notin
	s_mul_hi_u32 s40, s11, 14861479
	s_mul_i32 s42, s40, 289
	s_sub_u32 s41, s11, s42
	s_mul_i32 s42, s40, 2367488
	s_lshl_b32 s43, s41, 7
	s_add_u32 s42, s42, s43
	s_add_u32 s26, s12, s42
	s_addc_u32 s27, s13, 0
	s_mov_b32 s28, 36992
	s_lshl_b32 s45, s41, 5
	s_mov_b32 s46, s45
	s_cmpk_lt_u32 s45, 5120
	s_cbranch_scc1 .Ltup2_pro_drow_done
	s_movk_i32 s46, 9216
	s_cmpk_lt_u32 s45, 5152
	s_cbranch_scc1 .Ltup2_pro_drow_done
	s_sub_u32 s47, s45, 5152
	s_movk_i32 s43, 5120
	s_cmpk_lt_u32 s45, 7200
	s_cbranch_scc1 .Ltup2_pro_drow_cf
	s_sub_u32 s47, s45, 7200
	s_movk_i32 s43, 5248

; #define PG8_STAGE(bufoff, gbase, voff) do { _Pragma("unroll") for (int _i = 0; _i < 2; ++_i) \
;         __builtin_amdgcn_global_load_lds((const unsigned*)((const char*)(gbase) + (voff)[_i]), (PG8_LAS unsigned*)(lds + (bufoff) + ldsw + _i * 8192), 16, 0, 0); } while (0)
; #define PG8_LDA(dst, b, h) do { _Pragma("unroll") for (int m = 0; m < 4; ++m) _Pragma("unroll") for (int k = 0; k < 2; ++k) dst[m][k] = *(const PG8_LAS bf16x8*)(lds + PG8_SA(b, h) + aoff + m * 2048 + k * 1024); } while (0)
; #define PG8_LDB(dst, b, h) do { _Pragma("unroll") for (int n = 0; n < 2; ++n) _Pragma("unroll") for (int k = 0; k < 2; ++k) dst[n][k] = *(const PG8_LAS bf16x8*)(lds + PG8_SB(b, h) + boff + n * 2048 + k * 1024); } while (0)
; #define PG8_MMA(ai, bj, At, Bt) do { __builtin_amdgcn_s_setprio(1); _Pragma("unroll") for (int m = 0; m < 4; ++m) _Pragma("unroll") for (int n = 0; n < 2; ++n) _Pragma("unroll") for (int k = 0; k < 2; ++k) \
;         acc[ai][bj][m][n] = __builtin_amdgcn_mfma_f32_16x16x32_bf16(Bt[n][k], At[m][k], acc[ai][bj][m][n], 0, 0, 0); __builtin_amdgcn_s_setprio(0); } while (0)
; #define PG8_WAIT_V(n) asm volatile("s_waitcnt vmcnt(" #n ")" ::: "memory")
; #define PG8_WAIT_L(n) asm volatile("s_waitcnt lgkmcnt(" #n ")" ::: "memory")
; #define PG8_BAR __builtin_amdgcn_s_barrier()
; template <class Epi, class Sched, bool ALIGN_EPI = false, bool SP2 = false>
; __device__ __forceinline__ void gemm_phase(PG8_LAS unsigned char* lds, const Gemm g, const Sched& S, const Epi& E) {
;     ...
;         for (int t = 0; t < nt; t += 2) {
;             const bool last = (t == nt - 2);
;             const char* a1 = cA + (size_t)(t + 1) * kstep;
;             const char* a2 = last ? nA : cA + (size_t)(t + 2) * kstep; const char* b2 = last ? nB : cB + (size_t)(t + 2) * kstep;
;             const char* a3 = a2 + kstep; const char* b3 = b2 + kstep;
;             if constexpr (SP2) {
;             PG8_LDB(B0, 0, 0); PG8_LDB(B1, 0, 1); PG8_SCHED; PG8_LDA(At, 0, 0); PG8_STAGE(PG8_SA(1, 1), a1 + hstep, voffA);
;             PG8_WAIT_V(8); PG8_WAIT_L(0); PG8_BAR; PG8_MMA(0, 0, At, B0); PG8_MMA(0, 1, At, B1); PG8_BAR; PG8_SCHED;
;             PG8_LDA(At, 0, 1); PG8_STAGE(PG8_SB(0, 0), b2, voffB); PG8_STAGE(PG8_SB(0, 1), b2 + hstep, voffB); PG8_STAGE(PG8_SA(0, 0), a2, voffA);
;             PG8_WAIT_V(8); PG8_WAIT_L(0); PG8_BAR; PG8_MMA(1, 0, At, B0); PG8_MMA(1, 1, At, B1); PG8_BAR; PG8_SCHED;
.LBB0_814:
	ds_read_b128 v[144:147], v154
	ds_read_b128 v[158:161], v154 offset:1024
	ds_read_b128 v[162:165], v154 offset:2048
	ds_read_b128 v[166:169], v154 offset:3072
	ds_read_b128 v[170:173], v155
	ds_read_b128 v[174:177], v155 offset:1024
	ds_read_b128 v[178:181], v155 offset:2048
	ds_read_b128 v[182:185], v155 offset:3072
	s_add_i32 s17, s10, 2
	s_add_u32 s11, s8, 0xfff80080
	s_addc_u32 s12, s9, -1
	s_cmp_eq_u32 s14, s10
	s_cselect_b32 s10, s36, s15
	s_cselect_b32 s13, s35, s12
	s_cselect_b32 s12, s34, s11
	s_cselect_b32 s11, s37, s16
	v_lshl_add_u64 v[210:211], s[8:9], 0, v[138:139]
	s_add_i32 m0, s41, 0xc000
	ds_read_b128 v[186:189], v156
	ds_read_b128 v[190:193], v156 offset:1024
	ds_read_b128 v[194:197], v156 offset:2048
	ds_read_b128 v[198:201], v156 offset:3072
	ds_read_b128 v[202:205], v156 offset:4096
	ds_read_b128 v[206:209], v156 offset:5120
	ds_read_b128 v[214:217], v156 offset:6144
	ds_read_b128 v[218:221], v156 offset:7168
	global_load_lds_dwordx4 v[210:211], off
	v_lshl_add_u64 v[210:211], s[8:9], 0, v[140:141]
	s_add_i32 m0, s41, 0xe000
	s_nop 0
	global_load_lds_dwordx4 v[210:211], off
	s_waitcnt vmcnt(8)
	s_waitcnt lgkmcnt(0)
	s_barrier
	s_setprio 1
	s_waitcnt lgkmcnt(0)
	v_mfma_f32_16x16x32_bf16 v[124:127], v[144:147], v[186:189], v[124:127]
	v_mfma_f32_16x16x32_bf16 v[120:123], v[162:165], v[186:189], v[120:123]
	v_mfma_f32_16x16x32_bf16 v[108:111], v[144:147], v[194:197], v[108:111]
	v_mfma_f32_16x16x32_bf16 v[104:107], v[162:165], v[194:197], v[104:107]
	v_mfma_f32_16x16x32_bf16 v[92:95], v[144:147], v[202:205], v[92:95]
	v_mfma_f32_16x16x32_bf16 v[88:91], v[162:165], v[202:205], v[88:91]
	v_mfma_f32_16x16x32_bf16 v[76:79], v[144:147], v[214:217], v[76:79]
	v_mfma_f32_16x16x32_bf16 v[72:75], v[162:165], v[214:217], v[72:75]
	v_mfma_f32_16x16x32_bf16 v[124:127], v[158:161], v[190:193], v[124:127]
	v_mfma_f32_16x16x32_bf16 v[120:123], v[166:169], v[190:193], v[120:123]
	v_mfma_f32_16x16x32_bf16 v[108:111], v[158:161], v[198:201], v[108:111]
	v_mfma_f32_16x16x32_bf16 v[104:107], v[166:169], v[198:201], v[104:107]
	v_mfma_f32_16x16x32_bf16 v[92:95], v[158:161], v[206:209], v[92:95]
	v_mfma_f32_16x16x32_bf16 v[88:91], v[166:169], v[206:209], v[88:91]
	v_mfma_f32_16x16x32_bf16 v[76:79], v[158:161], v[218:221], v[76:79]
	v_mfma_f32_16x16x32_bf16 v[72:75], v[166:169], v[218:221], v[72:75]
	s_setprio 0
	s_setprio 1
	v_mfma_f32_16x16x32_bf16 v[116:119], v[170:173], v[186:189], v[116:119]
	v_mfma_f32_16x16x32_bf16 v[112:115], v[178:181], v[186:189], v[112:115]
	v_mfma_f32_16x16x32_bf16 v[100:103], v[170:173], v[194:197], v[100:103]
	v_mfma_f32_16x16x32_bf16 v[96:99], v[178:181], v[194:197], v[96:99]
	v_mfma_f32_16x16x32_bf16 v[84:87], v[170:173], v[202:205], v[84:87]
	v_mfma_f32_16x16x32_bf16 v[80:83], v[178:181], v[202:205], v[80:83]
	v_mfma_f32_16x16x32_bf16 v[68:71], v[170:173], v[214:217], v[68:71]
	v_mfma_f32_16x16x32_bf16 v[64:67], v[178:181], v[214:217], v[64:67]
	v_mfma_f32_16x16x32_bf16 v[116:119], v[174:177], v[190:193], v[116:119]
	v_mfma_f32_16x16x32_bf16 v[112:115], v[182:185], v[190:193], v[112:115]
	v_mfma_f32_16x16x32_bf16 v[100:103], v[174:177], v[198:201], v[100:103]
	v_mfma_f32_16x16x32_bf16 v[96:99], v[182:185], v[198:201], v[96:99]
	v_mfma_f32_16x16x32_bf16 v[84:87], v[174:177], v[206:209], v[84:87]
	v_mfma_f32_16x16x32_bf16 v[80:83], v[182:185], v[206:209], v[80:83]
	v_mfma_f32_16x16x32_bf16 v[68:71], v[174:177], v[218:221], v[68:71]
	v_mfma_f32_16x16x32_bf16 v[64:67], v[182:185], v[218:221], v[64:67]
	s_setprio 0
	s_barrier
	s_add_i32 s18, s50, s40
	v_lshl_add_u64 v[210:211], s[10:11], 0, v[130:131]
	s_mov_b32 m0, s18
	ds_read_b128 v[186:189], v156 offset:16384
	ds_read_b128 v[190:193], v156 offset:17408
	ds_read_b128 v[194:197], v156 offset:18432
	ds_read_b128 v[198:201], v156 offset:19456
	ds_read_b128 v[202:205], v156 offset:20480
	ds_read_b128 v[206:209], v156 offset:21504
	ds_read_b128 v[214:217], v156 offset:22528
	ds_read_b128 v[218:221], v156 offset:23552
	global_load_lds_dwordx4 v[210:211], off
	s_add_i32 m0, s18, 0x2000
	s_add_u32 s18, s10, 0x80000
	v_lshl_add_u64 v[222:223], s[10:11], 0, v[134:135]
	s_addc_u32 s19, s11, 0
	s_add_i32 s54, s51, s40
	global_load_lds_dwordx4 v[222:223], off
	v_lshl_add_u64 v[224:225], s[18:19], 0, v[130:131]
	s_mov_b32 m0, s54
	v_lshl_add_u64 v[226:227], s[12:13], 0, v[132:133]
	global_load_lds_dwordx4 v[224:225], off
	v_lshl_add_u64 v[224:225], s[18:19], 0, v[134:135]
	s_add_i32 m0, s54, 0x2000
	s_nop 0
	global_load_lds_dwordx4 v[224:225], off
	v_lshl_add_u64 v[224:225], s[12:13], 0, v[128:129]
	s_mov_b32 m0, s41
	s_nop 0
	global_load_lds_dwordx4 v[224:225], off
	s_mov_b32 m0, s42
	s_nop 0
	global_load_lds_dwordx4 v[226:227], off
	s_waitcnt vmcnt(8)
	s_waitcnt lgkmcnt(0)
	s_barrier
; #define PG8_STAGE(bufoff, gbase, voff) do { _Pragma("unroll") for (int _i = 0; _i < 2; ++_i) \
;         __builtin_amdgcn_global_load_lds((const unsigned*)((const char*)(gbase) + (voff)[_i]), (PG8_LAS unsigned*)(lds + (bufoff) + ldsw + _i * 8192), 16, 0, 0); } while (0)
; #define PG8_LDA(dst, b, h) do { _Pragma("unroll") for (int m = 0; m < 4; ++m) _Pragma("unroll") for (int k = 0; k < 2; ++k) dst[m][k] = *(const PG8_LAS bf16x8*)(lds + PG8_SA(b, h) + aoff + m * 2048 + k * 1024); } while (0)
; #define PG8_LDB(dst, b, h) do { _Pragma("unroll") for (int n = 0; n < 2; ++n) _Pragma("unroll") for (int k = 0; k < 2; ++k) dst[n][k] = *(const PG8_LAS bf16x8*)(lds + PG8_SB(b, h) + boff + n * 2048 + k * 1024); } while (0)
; #define PG8_MMA(ai, bj, At, Bt) do { __builtin_amdgcn_s_setprio(1); _Pragma("unroll") for (int m = 0; m < 4; ++m) _Pragma("unroll") for (int n = 0; n < 2; ++n) _Pragma("unroll") for (int k = 0; k < 2; ++k) \
;         acc[ai][bj][m][n] = __builtin_amdgcn_mfma_f32_16x16x32_bf16(Bt[n][k], At[m][k], acc[ai][bj][m][n], 0, 0, 0); __builtin_amdgcn_s_setprio(0); } while (0)
; #define PG8_WAIT_V(n) asm volatile("s_waitcnt vmcnt(" #n ")" ::: "memory")
; #define PG8_WAIT_L(n) asm volatile("s_waitcnt lgkmcnt(" #n ")" ::: "memory")
; #define PG8_BAR __builtin_amdgcn_s_barrier()
; #define PG8_SCHED __builtin_amdgcn_sched_barrier(0)
; template <class Epi, class Sched, bool ALIGN_EPI = false, bool SP2 = false>
; __device__ __forceinline__ void gemm_phase(PG8_LAS unsigned char* lds, const Gemm g, const Sched& S, const Epi& E) {
;     ...
;             PG8_WAIT_V(8); PG8_WAIT_L(0); PG8_BAR; PG8_MMA(1, 0, At, B0); PG8_MMA(1, 1, At, B1); PG8_BAR; PG8_SCHED;
;             PG8_LDB(B0, 1, 0); PG8_LDB(B1, 1, 1); PG8_SCHED; PG8_LDA(At, 1, 0); PG8_STAGE(PG8_SA(0, 1), a2 + hstep, voffA);
;             PG8_WAIT_V(8); PG8_WAIT_L(0); PG8_BAR; PG8_MMA(0, 0, At, B0); PG8_MMA(0, 1, At, B1); PG8_BAR; PG8_SCHED;
	s_setprio 1
	s_waitcnt lgkmcnt(0)
	v_mfma_f32_16x16x32_bf16 v[60:63], v[144:147], v[186:189], v[60:63]
	v_mfma_f32_16x16x32_bf16 v[56:59], v[162:165], v[186:189], v[56:59]
	v_mfma_f32_16x16x32_bf16 v[44:47], v[144:147], v[194:197], v[44:47]
	v_mfma_f32_16x16x32_bf16 v[40:43], v[162:165], v[194:197], v[40:43]
	v_mfma_f32_16x16x32_bf16 v[28:31], v[144:147], v[202:205], v[28:31]
	v_mfma_f32_16x16x32_bf16 v[24:27], v[162:165], v[202:205], v[24:27]
	v_mfma_f32_16x16x32_bf16 v[12:15], v[144:147], v[214:217], v[12:15]
	v_mfma_f32_16x16x32_bf16 v[8:11], v[162:165], v[214:217], v[8:11]
	v_mfma_f32_16x16x32_bf16 v[60:63], v[158:161], v[190:193], v[60:63]
	v_mfma_f32_16x16x32_bf16 v[56:59], v[166:169], v[190:193], v[56:59]
	v_mfma_f32_16x16x32_bf16 v[44:47], v[158:161], v[198:201], v[44:47]
	v_mfma_f32_16x16x32_bf16 v[40:43], v[166:169], v[198:201], v[40:43]
	v_mfma_f32_16x16x32_bf16 v[28:31], v[158:161], v[206:209], v[28:31]
	v_mfma_f32_16x16x32_bf16 v[24:27], v[166:169], v[206:209], v[24:27]
	v_mfma_f32_16x16x32_bf16 v[12:15], v[158:161], v[218:221], v[12:15]
	v_mfma_f32_16x16x32_bf16 v[8:11], v[166:169], v[218:221], v[8:11]
	s_setprio 0
	s_setprio 1
	v_mfma_f32_16x16x32_bf16 v[52:55], v[170:173], v[186:189], v[52:55]
	v_mfma_f32_16x16x32_bf16 v[48:51], v[178:181], v[186:189], v[48:51]
	v_mfma_f32_16x16x32_bf16 v[36:39], v[170:173], v[194:197], v[36:39]
	v_mfma_f32_16x16x32_bf16 v[32:35], v[178:181], v[194:197], v[32:35]
	v_mfma_f32_16x16x32_bf16 v[20:23], v[170:173], v[202:205], v[20:23]
	v_mfma_f32_16x16x32_bf16 v[16:19], v[178:181], v[202:205], v[16:19]
	v_mfma_f32_16x16x32_bf16 v[4:7], v[170:173], v[214:217], v[4:7]
	v_mfma_f32_16x16x32_bf16 v[0:3], v[178:181], v[214:217], v[0:3]
	v_mfma_f32_16x16x32_bf16 v[52:55], v[174:177], v[190:193], v[52:55]
	v_mfma_f32_16x16x32_bf16 v[48:51], v[182:185], v[190:193], v[48:51]
	v_mfma_f32_16x16x32_bf16 v[36:39], v[174:177], v[198:201], v[36:39]
	v_mfma_f32_16x16x32_bf16 v[32:35], v[182:185], v[198:201], v[32:35]
	v_mfma_f32_16x16x32_bf16 v[20:23], v[174:177], v[206:209], v[20:23]
	v_mfma_f32_16x16x32_bf16 v[16:19], v[182:185], v[206:209], v[16:19]
	v_mfma_f32_16x16x32_bf16 v[4:7], v[174:177], v[218:221], v[4:7]
	v_mfma_f32_16x16x32_bf16 v[0:3], v[182:185], v[218:221], v[0:3]
	s_setprio 0
	s_barrier
	s_add_i32 s18, 0, 0x18000
	v_add_u32_e32 v136, s18, v151
	s_add_i32 s19, 0, 0x1c000
	ds_read_b128 v[144:147], v136
	ds_read_b128 v[158:161], v136 offset:1024
	ds_read_b128 v[162:165], v136 offset:2048
	ds_read_b128 v[166:169], v136 offset:3072
	v_add_u32_e32 v136, s19, v151
	ds_read_b128 v[170:173], v136
	ds_read_b128 v[174:177], v136 offset:1024
	ds_read_b128 v[178:181], v136 offset:2048
	ds_read_b128 v[182:185], v136 offset:3072
	s_add_u32 s12, s12, 0x80000
	s_addc_u32 s13, s13, 0
	s_mov_b32 m0, s43
	v_lshl_add_u64 v[228:229], s[12:13], 0, v[128:129]
	ds_read_b128 v[186:189], v156 offset:32768
	ds_read_b128 v[190:193], v156 offset:33792
	ds_read_b128 v[194:197], v156 offset:34816
	ds_read_b128 v[198:201], v156 offset:35840
	ds_read_b128 v[202:205], v156 offset:36864
	ds_read_b128 v[206:209], v156 offset:37888
	ds_read_b128 v[214:217], v156 offset:38912
	ds_read_b128 v[218:221], v156 offset:39936
	global_load_lds_dwordx4 v[228:229], off
	v_lshl_add_u64 v[228:229], s[12:13], 0, v[132:133]
	s_mov_b32 m0, s44
	s_nop 0
	global_load_lds_dwordx4 v[228:229], off
	s_waitcnt vmcnt(8)
	s_waitcnt lgkmcnt(0)
	s_barrier
	s_setprio 1
	s_waitcnt lgkmcnt(0)
	v_mfma_f32_16x16x32_bf16 v[124:127], v[144:147], v[186:189], v[124:127]
	v_mfma_f32_16x16x32_bf16 v[120:123], v[162:165], v[186:189], v[120:123]
	v_mfma_f32_16x16x32_bf16 v[108:111], v[144:147], v[194:197], v[108:111]
	v_mfma_f32_16x16x32_bf16 v[104:107], v[162:165], v[194:197], v[104:107]
	v_mfma_f32_16x16x32_bf16 v[92:95], v[144:147], v[202:205], v[92:95]
	v_mfma_f32_16x16x32_bf16 v[88:91], v[162:165], v[202:205], v[88:91]
	v_mfma_f32_16x16x32_bf16 v[76:79], v[144:147], v[214:217], v[76:79]
	v_mfma_f32_16x16x32_bf16 v[72:75], v[162:165], v[214:217], v[72:75]
	v_mfma_f32_16x16x32_bf16 v[124:127], v[158:161], v[190:193], v[124:127]
	v_mfma_f32_16x16x32_bf16 v[120:123], v[166:169], v[190:193], v[120:123]
	v_mfma_f32_16x16x32_bf16 v[108:111], v[158:161], v[198:201], v[108:111]
	v_mfma_f32_16x16x32_bf16 v[104:107], v[166:169], v[198:201], v[104:107]
	v_mfma_f32_16x16x32_bf16 v[92:95], v[158:161], v[206:209], v[92:95]
	v_mfma_f32_16x16x32_bf16 v[88:91], v[166:169], v[206:209], v[88:91]
	v_mfma_f32_16x16x32_bf16 v[76:79], v[158:161], v[218:221], v[76:79]
	v_mfma_f32_16x16x32_bf16 v[72:75], v[166:169], v[218:221], v[72:75]
	s_setprio 0
	s_setprio 1
	v_mfma_f32_16x16x32_bf16 v[116:119], v[170:173], v[186:189], v[116:119]
	v_mfma_f32_16x16x32_bf16 v[112:115], v[178:181], v[186:189], v[112:115]
	v_mfma_f32_16x16x32_bf16 v[100:103], v[170:173], v[194:197], v[100:103]
	v_mfma_f32_16x16x32_bf16 v[96:99], v[178:181], v[194:197], v[96:99]
	v_mfma_f32_16x16x32_bf16 v[84:87], v[170:173], v[202:205], v[84:87]
	v_mfma_f32_16x16x32_bf16 v[80:83], v[178:181], v[202:205], v[80:83]
	v_mfma_f32_16x16x32_bf16 v[68:71], v[170:173], v[214:217], v[68:71]
	v_mfma_f32_16x16x32_bf16 v[64:67], v[178:181], v[214:217], v[64:67]
	v_mfma_f32_16x16x32_bf16 v[116:119], v[174:177], v[190:193], v[116:119]
	v_mfma_f32_16x16x32_bf16 v[112:115], v[182:185], v[190:193], v[112:115]
	v_mfma_f32_16x16x32_bf16 v[100:103], v[174:177], v[198:201], v[100:103]
	v_mfma_f32_16x16x32_bf16 v[96:99], v[182:185], v[198:201], v[96:99]
	v_mfma_f32_16x16x32_bf16 v[84:87], v[174:177], v[206:209], v[84:87]
	v_mfma_f32_16x16x32_bf16 v[80:83], v[182:185], v[206:209], v[80:83]
	v_mfma_f32_16x16x32_bf16 v[68:71], v[174:177], v[218:221], v[68:71]
	v_mfma_f32_16x16x32_bf16 v[64:67], v[182:185], v[218:221], v[64:67]
	s_setprio 0
	s_barrier
; #define PG8_STAGE(bufoff, gbase, voff) do { _Pragma("unroll") for (int _i = 0; _i < 2; ++_i) \
;         __builtin_amdgcn_global_load_lds((const unsigned*)((const char*)(gbase) + (voff)[_i]), (PG8_LAS unsigned*)(lds + (bufoff) + ldsw + _i * 8192), 16, 0, 0); } while (0)
; #define PG8_LDA(dst, b, h) do { _Pragma("unroll") for (int m = 0; m < 4; ++m) _Pragma("unroll") for (int k = 0; k < 2; ++k) dst[m][k] = *(const PG8_LAS bf16x8*)(lds + PG8_SA(b, h) + aoff + m * 2048 + k * 1024); } while (0)
; #define PG8_MMA(ai, bj, At, Bt) do { __builtin_amdgcn_s_setprio(1); _Pragma("unroll") for (int m = 0; m < 4; ++m) _Pragma("unroll") for (int n = 0; n < 2; ++n) _Pragma("unroll") for (int k = 0; k < 2; ++k) \
;         acc[ai][bj][m][n] = __builtin_amdgcn_mfma_f32_16x16x32_bf16(Bt[n][k], At[m][k], acc[ai][bj][m][n], 0, 0, 0); __builtin_amdgcn_s_setprio(0); } while (0)
; #define PG8_WAIT_V(n) asm volatile("s_waitcnt vmcnt(" #n ")" ::: "memory")
; #define PG8_WAIT_L(n) asm volatile("s_waitcnt lgkmcnt(" #n ")" ::: "memory")
; #define PG8_BAR __builtin_amdgcn_s_barrier()
; #define PG8_SCHED __builtin_amdgcn_sched_barrier(0)
; template <class Epi, class Sched, bool ALIGN_EPI = false, bool SP2 = false>
; __device__ __forceinline__ void gemm_phase(PG8_LAS unsigned char* lds, const Gemm g, const Sched& S, const Epi& E) {
;     ...
;         for (int t = 0; t < nt; t += 2) {
;     ...
;             PG8_LDA(At, 1, 1); PG8_STAGE(PG8_SB(1, 0), b3, voffB); PG8_STAGE(PG8_SB(1, 1), b3 + hstep, voffB); PG8_STAGE(PG8_SA(1, 0), a3, voffA);
;             PG8_WAIT_V(8); PG8_WAIT_L(0); PG8_BAR; PG8_MMA(1, 0, At, B0); PG8_MMA(1, 1, At, B1); PG8_BAR; PG8_SCHED;
	s_add_i32 s12, s18, s40
	v_lshl_add_u64 v[210:211], v[210:211], 0, s[26:27]
	s_mov_b32 m0, s12
	ds_read_b128 v[186:189], v156 offset:49152
	ds_read_b128 v[190:193], v156 offset:50176
	ds_read_b128 v[194:197], v156 offset:51200
	ds_read_b128 v[198:201], v156 offset:52224
	ds_read_b128 v[202:205], v156 offset:53248
	ds_read_b128 v[206:209], v156 offset:54272
	ds_read_b128 v[214:217], v156 offset:55296
	ds_read_b128 v[218:221], v156 offset:56320
	global_load_lds_dwordx4 v[210:211], off
	s_add_i32 m0, s12, 0x2000
	s_add_u32 s10, s10, 0x80080
	v_lshl_add_u64 v[210:211], v[222:223], 0, s[26:27]
	s_addc_u32 s11, s11, 0
	s_add_i32 s12, s19, s40
	global_load_lds_dwordx4 v[210:211], off
	v_lshl_add_u64 v[210:211], s[10:11], 0, v[130:131]
	s_mov_b32 m0, s12
	s_nop 0
	global_load_lds_dwordx4 v[210:211], off
	v_lshl_add_u64 v[210:211], s[10:11], 0, v[134:135]
	s_add_i32 m0, s12, 0x2000
	s_nop 0
	global_load_lds_dwordx4 v[210:211], off
	v_lshl_add_u64 v[210:211], v[224:225], 0, s[26:27]
	s_mov_b32 m0, s46
	s_nop 0
	global_load_lds_dwordx4 v[210:211], off
	v_lshl_add_u64 v[210:211], v[226:227], 0, s[26:27]
	s_mov_b32 m0, s47
	s_nop 0
	global_load_lds_dwordx4 v[210:211], off
	s_waitcnt vmcnt(8)
	s_waitcnt lgkmcnt(0)
	s_barrier
	s_setprio 1
	s_waitcnt lgkmcnt(0)
	v_mfma_f32_16x16x32_bf16 v[60:63], v[144:147], v[186:189], v[60:63]
	v_mfma_f32_16x16x32_bf16 v[56:59], v[162:165], v[186:189], v[56:59]
	v_mfma_f32_16x16x32_bf16 v[44:47], v[144:147], v[194:197], v[44:47]
	v_mfma_f32_16x16x32_bf16 v[40:43], v[162:165], v[194:197], v[40:43]
	v_mfma_f32_16x16x32_bf16 v[28:31], v[144:147], v[202:205], v[28:31]
	v_mfma_f32_16x16x32_bf16 v[24:27], v[162:165], v[202:205], v[24:27]
	v_mfma_f32_16x16x32_bf16 v[12:15], v[144:147], v[214:217], v[12:15]
	v_mfma_f32_16x16x32_bf16 v[8:11], v[162:165], v[214:217], v[8:11]
	v_mfma_f32_16x16x32_bf16 v[60:63], v[158:161], v[190:193], v[60:63]
	v_mfma_f32_16x16x32_bf16 v[56:59], v[166:169], v[190:193], v[56:59]
	v_mfma_f32_16x16x32_bf16 v[44:47], v[158:161], v[198:201], v[44:47]
	v_mfma_f32_16x16x32_bf16 v[40:43], v[166:169], v[198:201], v[40:43]
	v_mfma_f32_16x16x32_bf16 v[28:31], v[158:161], v[206:209], v[28:31]
	v_mfma_f32_16x16x32_bf16 v[24:27], v[166:169], v[206:209], v[24:27]
	v_mfma_f32_16x16x32_bf16 v[12:15], v[158:161], v[218:221], v[12:15]
	v_mfma_f32_16x16x32_bf16 v[8:11], v[166:169], v[218:221], v[8:11]
	s_setprio 0
	s_setprio 1
	v_mfma_f32_16x16x32_bf16 v[52:55], v[170:173], v[186:189], v[52:55]
	v_mfma_f32_16x16x32_bf16 v[48:51], v[178:181], v[186:189], v[48:51]
	v_mfma_f32_16x16x32_bf16 v[36:39], v[170:173], v[194:197], v[36:39]
	v_mfma_f32_16x16x32_bf16 v[32:35], v[178:181], v[194:197], v[32:35]
	v_mfma_f32_16x16x32_bf16 v[20:23], v[170:173], v[202:205], v[20:23]
	v_mfma_f32_16x16x32_bf16 v[16:19], v[178:181], v[202:205], v[16:19]
	v_mfma_f32_16x16x32_bf16 v[4:7], v[170:173], v[214:217], v[4:7]
	v_mfma_f32_16x16x32_bf16 v[0:3], v[178:181], v[214:217], v[0:3]
	v_mfma_f32_16x16x32_bf16 v[52:55], v[174:177], v[190:193], v[52:55]
	v_mfma_f32_16x16x32_bf16 v[48:51], v[182:185], v[190:193], v[48:51]
	v_mfma_f32_16x16x32_bf16 v[36:39], v[174:177], v[198:201], v[36:39]
	v_mfma_f32_16x16x32_bf16 v[32:35], v[182:185], v[198:201], v[32:35]
	v_mfma_f32_16x16x32_bf16 v[20:23], v[174:177], v[206:209], v[20:23]
	v_mfma_f32_16x16x32_bf16 v[16:19], v[182:185], v[206:209], v[16:19]
	v_mfma_f32_16x16x32_bf16 v[4:7], v[174:177], v[218:221], v[4:7]
	v_mfma_f32_16x16x32_bf16 v[0:3], v[182:185], v[218:221], v[0:3]
	s_setprio 0
	s_add_u32 s8, s8, 0x100
	s_addc_u32 s9, s9, 0
	s_add_u32 s15, s15, 0x100
	s_addc_u32 s16, s16, 0
	s_cmp_ge_u32 s17, s7
	s_mov_b32 s10, s17
	s_barrier
	s_cbranch_scc0 .LBB0_814

; __device__ __forceinline__ int win_dest_row(int n0) {
;     if (n0 < 5120) return n0;
;     if (n0 < 5152) return CDT + (n0 - 5120);
;     if (n0 < 7200) { const int c = n0 - 5152; return CCF + 256 * (c >> 7) + (c & 127); }
;     { const int c = n0 - 7200; return CCF + 256 * (c >> 7) + 128 + (c & 127); }
; }
; __global__ void __launch_bounds__(512, 2) mk_fwd(Args args) {
;     ...
;         constexpr int I_IN = (DM / 64) * (9248 / 32), I_OUT = (DMIX / 64) * (DM / 32), I_UP = (DM / 64) * (FF2 / 32), I_DN = (FF / 64) * (DM / 32);
;         constexpr int n_items0 = I_IN + I_OUT + I_UP + I_DN;
;         for (int it = gw; it < n_items0; it += NGW) {
;             int r = it;
;             if (r < I_IN) { const int nblk = 9248 / 32, kb = r / nblk, nb = r % nblk; p0_transpose_item(w_in, DM, 9248, WinT, 64 * kb, 32 * nb, win_dest_row(32 * nb), scr, lane); continue; } r -= I_IN;
;             if (r < I_OUT) { const int nblk = DM / 32, kb = r / nblk, nb = r % nblk; p0_transpose_item(w_out, DMIX, DM, WoutT, 64 * kb, 32 * nb, 32 * nb, scr, lane); continue; } r -= I_OUT;
;             if (r < I_UP) { const int nblk = FF2 / 32, kb = r / nblk, nb = r % nblk; p0_transpose_item(w_up, DM, FF2, WupT, 64 * kb, 32 * nb, 32 * nb, scr, lane, norm_ffn_w); continue; } r -= I_UP;
;             { const int nblk = DM / 32, kb = r / nblk, nb = r % nblk; p0_transpose_item(w_down, FF, DM, WdnT, 64 * kb, 32 * nb, 32 * nb, scr, lane); }
.LBB0_822:
	v_writelane_b32 v254, s3, 0
	v_writelane_b32 v254, s4, 1
	v_writelane_b32 v254, s8, 2
	v_writelane_b32 v254, s9, 3
	v_writelane_b32 v254, s10, 4
	v_writelane_b32 v254, s11, 5
	v_writelane_b32 v254, s12, 6
	v_writelane_b32 v254, s13, 7
	v_writelane_b32 v254, s14, 8
	v_writelane_b32 v254, s15, 9
	v_writelane_b32 v254, s16, 10
	v_writelane_b32 v254, s17, 11
	v_writelane_b32 v254, s18, 12
	v_writelane_b32 v254, s19, 13
	v_writelane_b32 v254, s20, 14
	v_writelane_b32 v254, s21, 15
	v_writelane_b32 v254, s22, 16
	v_writelane_b32 v254, s23, 17
	v_writelane_b32 v254, s24, 18
	v_writelane_b32 v254, s25, 19
	v_writelane_b32 v254, s26, 20
	v_writelane_b32 v254, s27, 21
	v_writelane_b32 v254, s28, 22
	v_writelane_b32 v254, s29, 23
	v_writelane_b32 v254, s30, 24
	v_writelane_b32 v254, s31, 25
	v_writelane_b32 v254, s32, 26
	v_writelane_b32 v254, s33, 27
	v_writelane_b32 v254, s34, 28
	v_writelane_b32 v254, s35, 29
	v_writelane_b32 v254, s36, 30
	v_writelane_b32 v254, s37, 31
	v_writelane_b32 v254, s38, 32
	v_writelane_b32 v254, s39, 33
	v_writelane_b32 v254, s40, 34
	v_writelane_b32 v254, s41, 35
	v_writelane_b32 v254, s42, 36
	v_writelane_b32 v254, s43, 37
	v_writelane_b32 v254, s44, 38
	v_writelane_b32 v254, s45, 39
	v_writelane_b32 v254, s46, 40
	v_writelane_b32 v254, s47, 41
	v_writelane_b32 v254, s48, 42
	v_writelane_b32 v254, s49, 43
	v_writelane_b32 v254, s50, 44
	v_writelane_b32 v254, s51, 45
	v_writelane_b32 v254, s52, 46
	v_writelane_b32 v254, s53, 47
	v_writelane_b32 v254, s54, 48
	v_writelane_b32 v254, s55, 49
	s_cmpk_lt_u32 s2, 182
	s_cbranch_scc1 .Ltdn_skip
	s_mov_b64 s[8:9], s[96:97]
	v_and_b32_e32 v3, 63, v212
	v_readfirstlane_b32 s4, v212
	s_sub_u32 s3, s2, 182
	s_lshl_b32 s3, s3, 3
	s_lshr_b32 s4, s4, 6
	s_add_u32 s3, s3, s4
	s_add_u32 s11, s3, 24352
	s_sub_u32 s10, s94, 182
	s_lshl_b32 s10, s10, 3
	s_cmpk_lt_u32 s11, 29856
	s_cbranch_scc0 .Ltdn_skip
	s_load_dwordx2 s[12:13], s[8:9], 0x38
	s_load_dwordx2 s[14:15], s[8:9], 0x90
	s_load_dwordx2 s[16:17], s[8:9], 0xa0
	s_load_dwordx2 s[18:19], s[8:9], 0xb8
	s_load_dwordx2 s[20:21], s[8:9], 0x98
	s_load_dwordx2 s[22:23], s[8:9], 0xd0
	v_lshrrev_b32_e32 v4, 3, v3
	v_and_b32_e32 v7, 7, v3
	v_lshlrev_b32_e32 v5, 4, v7
	v_lshlrev_b32_e32 v6, 5, v7
	s_lshl_b32 s24, s4, 14
	v_lshl_add_u32 v16, v4, 7, s24
	v_xor_b32_e32 v8, 0, v7
	v_lshl_add_u32 v8, v8, 4, v16
	v_xor_b32_e32 v9, 1, v7
	v_lshl_add_u32 v9, v9, 4, v16
	v_xor_b32_e32 v10, 2, v7
	v_lshl_add_u32 v10, v10, 4, v16
	v_xor_b32_e32 v11, 3, v7
	v_lshl_add_u32 v11, v11, 4, v16
	v_xor_b32_e32 v12, 4, v7
	v_lshl_add_u32 v12, v12, 4, v16
	v_xor_b32_e32 v13, 5, v7
	v_lshl_add_u32 v13, v13, 4, v16
	v_xor_b32_e32 v14, 6, v7
	v_lshl_add_u32 v14, v14, 4, v16
	v_xor_b32_e32 v15, 7, v7
	v_lshl_add_u32 v15, v15, 4, v16
	v_lshlrev_b32_e32 v20, 2, v7
	v_lshl_add_u32 v21, v7, 10, s24
	v_add_u32_e32 v16, 0, v4
	v_xor_b32_e32 v16, v16, v20
	v_lshl_add_u32 v16, v16, 2, v21
	v_add_u32_e32 v17, 8, v4
	v_xor_b32_e32 v17, v17, v20
	v_lshl_add_u32 v17, v17, 2, v21
	v_add_u32_e32 v18, 16, v4
	v_xor_b32_e32 v18, v18, v20
	v_lshl_add_u32 v18, v18, 2, v21
	v_add_u32_e32 v19, 24, v4
	v_xor_b32_e32 v19, v19, v20
	v_lshl_add_u32 v19, v19, 2, v21
	s_waitcnt lgkmcnt(0)
	s_cmpk_lt_u32 s11, 9248
	s_cbranch_scc0 .Ltdn_pro_notin
	s_mul_hi_u32 s40, s11, 14861479
	s_mul_i32 s42, s40, 289
	s_sub_u32 s41, s11, s42
	s_mul_i32 s42, s40, 2367488
	s_lshl_b32 s43, s41, 7
	s_add_u32 s42, s42, s43
	s_add_u32 s26, s12, s42
	s_addc_u32 s27, s13, 0
	s_mov_b32 s28, 36992
	s_lshl_b32 s45, s41, 5
	s_mov_b32 s46, s45
	s_cmpk_lt_u32 s45, 5120
	s_cbranch_scc1 .Ltdn_pro_drow_done
	s_movk_i32 s46, 9216
	s_cmpk_lt_u32 s45, 5152
	s_cbranch_scc1 .Ltdn_pro_drow_done
	s_sub_u32 s47, s45, 5152
	s_movk_i32 s43, 5120
	s_cmpk_lt_u32 s45, 7200
	s_cbranch_scc1 .Ltdn_pro_drow_cf
	s_sub_u32 s47, s45, 7200
	s_movk_i32 s43, 5248

; #define PG8_STAGE(bufoff, gbase, voff) do { _Pragma("unroll") for (int _i = 0; _i < 2; ++_i) \
;         __builtin_amdgcn_global_load_lds((const unsigned*)((const char*)(gbase) + (voff)[_i]), (PG8_LAS unsigned*)(lds + (bufoff) + ldsw + _i * 8192), 16, 0, 0); } while (0)
; #define PG8_LDA(dst, b, h) do { _Pragma("unroll") for (int m = 0; m < 4; ++m) _Pragma("unroll") for (int k = 0; k < 2; ++k) dst[m][k] = *(const PG8_LAS bf16x8*)(lds + PG8_SA(b, h) + aoff + m * 2048 + k * 1024); } while (0)
; #define PG8_LDB(dst, b, h) do { _Pragma("unroll") for (int n = 0; n < 2; ++n) _Pragma("unroll") for (int k = 0; k < 2; ++k) dst[n][k] = *(const PG8_LAS bf16x8*)(lds + PG8_SB(b, h) + boff + n * 2048 + k * 1024); } while (0)
; #define PG8_MMA(ai, bj, At, Bt) do { __builtin_amdgcn_s_setprio(1); _Pragma("unroll") for (int m = 0; m < 4; ++m) _Pragma("unroll") for (int n = 0; n < 2; ++n) _Pragma("unroll") for (int k = 0; k < 2; ++k) \
;         acc[ai][bj][m][n] = __builtin_amdgcn_mfma_f32_16x16x32_bf16(Bt[n][k], At[m][k], acc[ai][bj][m][n], 0, 0, 0); __builtin_amdgcn_s_setprio(0); } while (0)
; #define PG8_WAIT_V(n) asm volatile("s_waitcnt vmcnt(" #n ")" ::: "memory")
; #define PG8_WAIT_L(n) asm volatile("s_waitcnt lgkmcnt(" #n ")" ::: "memory")
; #define PG8_BAR __builtin_amdgcn_s_barrier()
; template <class Epi, class Sched, bool ALIGN_EPI = false, bool SP2 = false>
; __device__ __forceinline__ void gemm_phase(PG8_LAS unsigned char* lds, const Gemm g, const Sched& S, const Epi& E) {
;     ...
;         for (int t = 0; t < nt; t += 2) {
;             const bool last = (t == nt - 2);
;             const char* a1 = cA + (size_t)(t + 1) * kstep;
;             const char* a2 = last ? nA : cA + (size_t)(t + 2) * kstep; const char* b2 = last ? nB : cB + (size_t)(t + 2) * kstep;
;             const char* a3 = a2 + kstep; const char* b3 = b2 + kstep;
;             if constexpr (SP2) {
;             PG8_LDB(B0, 0, 0); PG8_LDB(B1, 0, 1); PG8_SCHED; PG8_LDA(At, 0, 0); PG8_STAGE(PG8_SA(1, 1), a1 + hstep, voffA);
;             PG8_WAIT_V(8); PG8_WAIT_L(0); PG8_BAR; PG8_MMA(0, 0, At, B0); PG8_MMA(0, 1, At, B1); PG8_BAR; PG8_SCHED;
;             PG8_LDA(At, 0, 1); PG8_STAGE(PG8_SB(0, 0), b2, voffB); PG8_STAGE(PG8_SB(0, 1), b2 + hstep, voffB); PG8_STAGE(PG8_SA(0, 0), a2, voffA);
;             PG8_WAIT_V(8); PG8_WAIT_L(0); PG8_BAR; PG8_MMA(1, 0, At, B0); PG8_MMA(1, 1, At, B1); PG8_BAR; PG8_SCHED;
.LBB0_976:
	ds_read_b128 v[144:147], v151
	ds_read_b128 v[154:157], v151 offset:1024
	ds_read_b128 v[158:161], v151 offset:2048
	ds_read_b128 v[162:165], v151 offset:3072
	ds_read_b128 v[166:169], v152
	ds_read_b128 v[170:173], v152 offset:1024
	ds_read_b128 v[174:177], v152 offset:2048
	ds_read_b128 v[178:181], v152 offset:3072
	s_add_i32 s79, s36, 2
	s_add_u32 s34, s30, 0x100
	s_addc_u32 s35, s31, 0
	s_cmp_eq_u32 s14, s36
	s_cselect_b32 s36, s26, s77
	s_cselect_b32 s39, s25, s35
	s_cselect_b32 s38, s24, s34
	s_cselect_b32 s37, s27, s78
	v_lshl_add_u64 v[210:211], s[30:31], 0, v[138:139]
	s_add_i32 m0, s43, 0xc000
	ds_read_b128 v[182:185], v153
	ds_read_b128 v[186:189], v153 offset:1024
	ds_read_b128 v[190:193], v153 offset:2048
	ds_read_b128 v[194:197], v153 offset:3072
	ds_read_b128 v[198:201], v153 offset:4096
	ds_read_b128 v[202:205], v153 offset:5120
	ds_read_b128 v[206:209], v153 offset:6144
	ds_read_b128 v[214:217], v153 offset:7168
	global_load_lds_dwordx4 v[210:211], off
	v_lshl_add_u64 v[210:211], s[30:31], 0, v[140:141]
	s_add_i32 m0, s43, 0xe000
	s_nop 0
	global_load_lds_dwordx4 v[210:211], off
	s_waitcnt vmcnt(8)
	s_waitcnt lgkmcnt(0)
	s_barrier
	s_setprio 1
	s_waitcnt lgkmcnt(0)
	v_mfma_f32_16x16x32_bf16 v[124:127], v[144:147], v[182:185], v[124:127]
	v_mfma_f32_16x16x32_bf16 v[120:123], v[158:161], v[182:185], v[120:123]
	v_mfma_f32_16x16x32_bf16 v[108:111], v[144:147], v[190:193], v[108:111]
	v_mfma_f32_16x16x32_bf16 v[104:107], v[158:161], v[190:193], v[104:107]
	v_mfma_f32_16x16x32_bf16 v[92:95], v[144:147], v[198:201], v[92:95]
	v_mfma_f32_16x16x32_bf16 v[88:91], v[158:161], v[198:201], v[88:91]
	v_mfma_f32_16x16x32_bf16 v[76:79], v[144:147], v[206:209], v[76:79]
	v_mfma_f32_16x16x32_bf16 v[72:75], v[158:161], v[206:209], v[72:75]
	v_mfma_f32_16x16x32_bf16 v[124:127], v[154:157], v[186:189], v[124:127]
	v_mfma_f32_16x16x32_bf16 v[120:123], v[162:165], v[186:189], v[120:123]
	v_mfma_f32_16x16x32_bf16 v[108:111], v[154:157], v[194:197], v[108:111]
	v_mfma_f32_16x16x32_bf16 v[104:107], v[162:165], v[194:197], v[104:107]
	v_mfma_f32_16x16x32_bf16 v[92:95], v[154:157], v[202:205], v[92:95]
	v_mfma_f32_16x16x32_bf16 v[88:91], v[162:165], v[202:205], v[88:91]
	v_mfma_f32_16x16x32_bf16 v[76:79], v[154:157], v[214:217], v[76:79]
	v_mfma_f32_16x16x32_bf16 v[72:75], v[162:165], v[214:217], v[72:75]
	s_setprio 0
	s_setprio 1
	v_mfma_f32_16x16x32_bf16 v[116:119], v[166:169], v[182:185], v[116:119]
	v_mfma_f32_16x16x32_bf16 v[112:115], v[174:177], v[182:185], v[112:115]
	v_mfma_f32_16x16x32_bf16 v[100:103], v[166:169], v[190:193], v[100:103]
	v_mfma_f32_16x16x32_bf16 v[96:99], v[174:177], v[190:193], v[96:99]
	v_mfma_f32_16x16x32_bf16 v[84:87], v[166:169], v[198:201], v[84:87]
	v_mfma_f32_16x16x32_bf16 v[80:83], v[174:177], v[198:201], v[80:83]
	v_mfma_f32_16x16x32_bf16 v[68:71], v[166:169], v[206:209], v[68:71]
	v_mfma_f32_16x16x32_bf16 v[64:67], v[174:177], v[206:209], v[64:67]
	v_mfma_f32_16x16x32_bf16 v[116:119], v[170:173], v[186:189], v[116:119]
	v_mfma_f32_16x16x32_bf16 v[112:115], v[178:181], v[186:189], v[112:115]
	v_mfma_f32_16x16x32_bf16 v[100:103], v[170:173], v[194:197], v[100:103]
	v_mfma_f32_16x16x32_bf16 v[96:99], v[178:181], v[194:197], v[96:99]
	v_mfma_f32_16x16x32_bf16 v[84:87], v[170:173], v[202:205], v[84:87]
	v_mfma_f32_16x16x32_bf16 v[80:83], v[178:181], v[202:205], v[80:83]
	v_mfma_f32_16x16x32_bf16 v[68:71], v[170:173], v[214:217], v[68:71]
	v_mfma_f32_16x16x32_bf16 v[64:67], v[178:181], v[214:217], v[64:67]
	s_setprio 0
	s_barrier
	s_add_i32 s30, s55, s42
	v_lshl_add_u64 v[210:211], s[36:37], 0, v[130:131]
	s_mov_b32 m0, s30
	ds_read_b128 v[182:185], v153 offset:16384
	ds_read_b128 v[186:189], v153 offset:17408
	ds_read_b128 v[190:193], v153 offset:18432
	ds_read_b128 v[194:197], v153 offset:19456
	ds_read_b128 v[198:201], v153 offset:20480
	ds_read_b128 v[202:205], v153 offset:21504
	ds_read_b128 v[206:209], v153 offset:22528
	ds_read_b128 v[214:217], v153 offset:23552
	global_load_lds_dwordx4 v[210:211], off
	s_add_i32 m0, s30, 0x2000
	s_add_u32 s30, s36, 0x158000
	v_lshl_add_u64 v[218:219], s[36:37], 0, v[134:135]
	s_addc_u32 s31, s37, 0
	s_add_i32 s80, s56, s42
	global_load_lds_dwordx4 v[218:219], off
	v_lshl_add_u64 v[220:221], s[30:31], 0, v[130:131]
	s_mov_b32 m0, s80
	v_lshl_add_u64 v[222:223], s[38:39], 0, v[132:133]
	global_load_lds_dwordx4 v[220:221], off
	v_lshl_add_u64 v[220:221], s[30:31], 0, v[134:135]
	s_add_i32 m0, s80, 0x2000
	s_nop 0
	global_load_lds_dwordx4 v[220:221], off
	v_lshl_add_u64 v[220:221], s[38:39], 0, v[128:129]
	s_mov_b32 m0, s43
	s_nop 0
	global_load_lds_dwordx4 v[220:221], off
	s_mov_b32 m0, s44
	s_nop 0
	global_load_lds_dwordx4 v[222:223], off
	s_waitcnt vmcnt(8)
	s_waitcnt lgkmcnt(0)
	s_barrier
; #define PG8_STAGE(bufoff, gbase, voff) do { _Pragma("unroll") for (int _i = 0; _i < 2; ++_i) \
;         __builtin_amdgcn_global_load_lds((const unsigned*)((const char*)(gbase) + (voff)[_i]), (PG8_LAS unsigned*)(lds + (bufoff) + ldsw + _i * 8192), 16, 0, 0); } while (0)
; #define PG8_LDA(dst, b, h) do { _Pragma("unroll") for (int m = 0; m < 4; ++m) _Pragma("unroll") for (int k = 0; k < 2; ++k) dst[m][k] = *(const PG8_LAS bf16x8*)(lds + PG8_SA(b, h) + aoff + m * 2048 + k * 1024); } while (0)
; #define PG8_LDB(dst, b, h) do { _Pragma("unroll") for (int n = 0; n < 2; ++n) _Pragma("unroll") for (int k = 0; k < 2; ++k) dst[n][k] = *(const PG8_LAS bf16x8*)(lds + PG8_SB(b, h) + boff + n * 2048 + k * 1024); } while (0)
; #define PG8_MMA(ai, bj, At, Bt) do { __builtin_amdgcn_s_setprio(1); _Pragma("unroll") for (int m = 0; m < 4; ++m) _Pragma("unroll") for (int n = 0; n < 2; ++n) _Pragma("unroll") for (int k = 0; k < 2; ++k) \
;         acc[ai][bj][m][n] = __builtin_amdgcn_mfma_f32_16x16x32_bf16(Bt[n][k], At[m][k], acc[ai][bj][m][n], 0, 0, 0); __builtin_amdgcn_s_setprio(0); } while (0)
; #define PG8_WAIT_V(n) asm volatile("s_waitcnt vmcnt(" #n ")" ::: "memory")
; #define PG8_WAIT_L(n) asm volatile("s_waitcnt lgkmcnt(" #n ")" ::: "memory")
; #define PG8_BAR __builtin_amdgcn_s_barrier()
; #define PG8_SCHED __builtin_amdgcn_sched_barrier(0)
; template <class Epi, class Sched, bool ALIGN_EPI = false, bool SP2 = false>
; __device__ __forceinline__ void gemm_phase(PG8_LAS unsigned char* lds, const Gemm g, const Sched& S, const Epi& E) {
;     ...
;             PG8_WAIT_V(8); PG8_WAIT_L(0); PG8_BAR; PG8_MMA(1, 0, At, B0); PG8_MMA(1, 1, At, B1); PG8_BAR; PG8_SCHED;
;             PG8_LDB(B0, 1, 0); PG8_LDB(B1, 1, 1); PG8_SCHED; PG8_LDA(At, 1, 0); PG8_STAGE(PG8_SA(0, 1), a2 + hstep, voffA);
;             PG8_WAIT_V(8); PG8_WAIT_L(0); PG8_BAR; PG8_MMA(0, 0, At, B0); PG8_MMA(0, 1, At, B1); PG8_BAR; PG8_SCHED;
	s_setprio 1
	s_waitcnt lgkmcnt(0)
	v_mfma_f32_16x16x32_bf16 v[60:63], v[144:147], v[182:185], v[60:63]
	v_mfma_f32_16x16x32_bf16 v[56:59], v[158:161], v[182:185], v[56:59]
	v_mfma_f32_16x16x32_bf16 v[44:47], v[144:147], v[190:193], v[44:47]
	v_mfma_f32_16x16x32_bf16 v[40:43], v[158:161], v[190:193], v[40:43]
	v_mfma_f32_16x16x32_bf16 v[28:31], v[144:147], v[198:201], v[28:31]
	v_mfma_f32_16x16x32_bf16 v[24:27], v[158:161], v[198:201], v[24:27]
	v_mfma_f32_16x16x32_bf16 v[12:15], v[144:147], v[206:209], v[12:15]
	v_mfma_f32_16x16x32_bf16 v[8:11], v[158:161], v[206:209], v[8:11]
	v_mfma_f32_16x16x32_bf16 v[60:63], v[154:157], v[186:189], v[60:63]
	v_mfma_f32_16x16x32_bf16 v[56:59], v[162:165], v[186:189], v[56:59]
	v_mfma_f32_16x16x32_bf16 v[44:47], v[154:157], v[194:197], v[44:47]
	v_mfma_f32_16x16x32_bf16 v[40:43], v[162:165], v[194:197], v[40:43]
	v_mfma_f32_16x16x32_bf16 v[28:31], v[154:157], v[202:205], v[28:31]
	v_mfma_f32_16x16x32_bf16 v[24:27], v[162:165], v[202:205], v[24:27]
	v_mfma_f32_16x16x32_bf16 v[12:15], v[154:157], v[214:217], v[12:15]
	v_mfma_f32_16x16x32_bf16 v[8:11], v[162:165], v[214:217], v[8:11]
	s_setprio 0
	s_setprio 1
	v_mfma_f32_16x16x32_bf16 v[52:55], v[166:169], v[182:185], v[52:55]
	v_mfma_f32_16x16x32_bf16 v[48:51], v[174:177], v[182:185], v[48:51]
	v_mfma_f32_16x16x32_bf16 v[36:39], v[166:169], v[190:193], v[36:39]
	v_mfma_f32_16x16x32_bf16 v[32:35], v[174:177], v[190:193], v[32:35]
	v_mfma_f32_16x16x32_bf16 v[20:23], v[166:169], v[198:201], v[20:23]
	v_mfma_f32_16x16x32_bf16 v[16:19], v[174:177], v[198:201], v[16:19]
	v_mfma_f32_16x16x32_bf16 v[4:7], v[166:169], v[206:209], v[4:7]
	v_mfma_f32_16x16x32_bf16 v[0:3], v[174:177], v[206:209], v[0:3]
	v_mfma_f32_16x16x32_bf16 v[52:55], v[170:173], v[186:189], v[52:55]
	v_mfma_f32_16x16x32_bf16 v[48:51], v[178:181], v[186:189], v[48:51]
	v_mfma_f32_16x16x32_bf16 v[36:39], v[170:173], v[194:197], v[36:39]
	v_mfma_f32_16x16x32_bf16 v[32:35], v[178:181], v[194:197], v[32:35]
	v_mfma_f32_16x16x32_bf16 v[20:23], v[170:173], v[202:205], v[20:23]
	v_mfma_f32_16x16x32_bf16 v[16:19], v[178:181], v[202:205], v[16:19]
	v_mfma_f32_16x16x32_bf16 v[4:7], v[170:173], v[214:217], v[4:7]
	v_mfma_f32_16x16x32_bf16 v[0:3], v[178:181], v[214:217], v[0:3]
	s_setprio 0
	s_barrier
	s_add_i32 s80, 0, 0x18000
	v_add_u32_e32 v136, s80, v149
	s_add_i32 s81, 0, 0x1c000
	ds_read_b128 v[144:147], v136
	ds_read_b128 v[154:157], v136 offset:1024
	ds_read_b128 v[158:161], v136 offset:2048
	ds_read_b128 v[162:165], v136 offset:3072
	v_add_u32_e32 v136, s81, v149
	ds_read_b128 v[166:169], v136
	ds_read_b128 v[170:173], v136 offset:1024
	ds_read_b128 v[174:177], v136 offset:2048
	ds_read_b128 v[178:181], v136 offset:3072
	s_add_u32 s30, s38, 0x158000
	s_addc_u32 s31, s39, 0
	s_mov_b32 m0, s45
	v_lshl_add_u64 v[224:225], s[30:31], 0, v[128:129]
	ds_read_b128 v[182:185], v153 offset:32768
	ds_read_b128 v[186:189], v153 offset:33792
	ds_read_b128 v[190:193], v153 offset:34816
	ds_read_b128 v[194:197], v153 offset:35840
	ds_read_b128 v[198:201], v153 offset:36864
	ds_read_b128 v[202:205], v153 offset:37888
	ds_read_b128 v[206:209], v153 offset:38912
	ds_read_b128 v[214:217], v153 offset:39936
	global_load_lds_dwordx4 v[224:225], off
	v_lshl_add_u64 v[224:225], s[30:31], 0, v[132:133]
	s_mov_b32 m0, s46
	s_nop 0
	global_load_lds_dwordx4 v[224:225], off
	s_waitcnt vmcnt(8)
	s_waitcnt lgkmcnt(0)
	s_barrier
	s_setprio 1
	s_waitcnt lgkmcnt(0)
	v_mfma_f32_16x16x32_bf16 v[124:127], v[144:147], v[182:185], v[124:127]
	v_mfma_f32_16x16x32_bf16 v[120:123], v[158:161], v[182:185], v[120:123]
	v_mfma_f32_16x16x32_bf16 v[108:111], v[144:147], v[190:193], v[108:111]
	v_mfma_f32_16x16x32_bf16 v[104:107], v[158:161], v[190:193], v[104:107]
	v_mfma_f32_16x16x32_bf16 v[92:95], v[144:147], v[198:201], v[92:95]
	v_mfma_f32_16x16x32_bf16 v[88:91], v[158:161], v[198:201], v[88:91]
	v_mfma_f32_16x16x32_bf16 v[76:79], v[144:147], v[206:209], v[76:79]
	v_mfma_f32_16x16x32_bf16 v[72:75], v[158:161], v[206:209], v[72:75]
	v_mfma_f32_16x16x32_bf16 v[124:127], v[154:157], v[186:189], v[124:127]
	v_mfma_f32_16x16x32_bf16 v[120:123], v[162:165], v[186:189], v[120:123]
	v_mfma_f32_16x16x32_bf16 v[108:111], v[154:157], v[194:197], v[108:111]
	v_mfma_f32_16x16x32_bf16 v[104:107], v[162:165], v[194:197], v[104:107]
	v_mfma_f32_16x16x32_bf16 v[92:95], v[154:157], v[202:205], v[92:95]
	v_mfma_f32_16x16x32_bf16 v[88:91], v[162:165], v[202:205], v[88:91]
	v_mfma_f32_16x16x32_bf16 v[76:79], v[154:157], v[214:217], v[76:79]
	v_mfma_f32_16x16x32_bf16 v[72:75], v[162:165], v[214:217], v[72:75]
	s_setprio 0
	s_setprio 1
	v_mfma_f32_16x16x32_bf16 v[116:119], v[166:169], v[182:185], v[116:119]
	v_mfma_f32_16x16x32_bf16 v[112:115], v[174:177], v[182:185], v[112:115]
	v_mfma_f32_16x16x32_bf16 v[100:103], v[166:169], v[190:193], v[100:103]
	v_mfma_f32_16x16x32_bf16 v[96:99], v[174:177], v[190:193], v[96:99]
	v_mfma_f32_16x16x32_bf16 v[84:87], v[166:169], v[198:201], v[84:87]
	v_mfma_f32_16x16x32_bf16 v[80:83], v[174:177], v[198:201], v[80:83]
	v_mfma_f32_16x16x32_bf16 v[68:71], v[166:169], v[206:209], v[68:71]
	v_mfma_f32_16x16x32_bf16 v[64:67], v[174:177], v[206:209], v[64:67]
	v_mfma_f32_16x16x32_bf16 v[116:119], v[170:173], v[186:189], v[116:119]
	v_mfma_f32_16x16x32_bf16 v[112:115], v[178:181], v[186:189], v[112:115]
	v_mfma_f32_16x16x32_bf16 v[100:103], v[170:173], v[194:197], v[100:103]
	v_mfma_f32_16x16x32_bf16 v[96:99], v[178:181], v[194:197], v[96:99]
	v_mfma_f32_16x16x32_bf16 v[84:87], v[170:173], v[202:205], v[84:87]
	v_mfma_f32_16x16x32_bf16 v[80:83], v[178:181], v[202:205], v[80:83]
	v_mfma_f32_16x16x32_bf16 v[68:71], v[170:173], v[214:217], v[68:71]
	v_mfma_f32_16x16x32_bf16 v[64:67], v[178:181], v[214:217], v[64:67]
	s_setprio 0
	s_barrier
; #define PG8_STAGE(bufoff, gbase, voff) do { _Pragma("unroll") for (int _i = 0; _i < 2; ++_i) \
;         __builtin_amdgcn_global_load_lds((const unsigned*)((const char*)(gbase) + (voff)[_i]), (PG8_LAS unsigned*)(lds + (bufoff) + ldsw + _i * 8192), 16, 0, 0); } while (0)
; #define PG8_LDA(dst, b, h) do { _Pragma("unroll") for (int m = 0; m < 4; ++m) _Pragma("unroll") for (int k = 0; k < 2; ++k) dst[m][k] = *(const PG8_LAS bf16x8*)(lds + PG8_SA(b, h) + aoff + m * 2048 + k * 1024); } while (0)
; #define PG8_MMA(ai, bj, At, Bt) do { __builtin_amdgcn_s_setprio(1); _Pragma("unroll") for (int m = 0; m < 4; ++m) _Pragma("unroll") for (int n = 0; n < 2; ++n) _Pragma("unroll") for (int k = 0; k < 2; ++k) \
;         acc[ai][bj][m][n] = __builtin_amdgcn_mfma_f32_16x16x32_bf16(Bt[n][k], At[m][k], acc[ai][bj][m][n], 0, 0, 0); __builtin_amdgcn_s_setprio(0); } while (0)
; #define PG8_WAIT_V(n) asm volatile("s_waitcnt vmcnt(" #n ")" ::: "memory")
; #define PG8_WAIT_L(n) asm volatile("s_waitcnt lgkmcnt(" #n ")" ::: "memory")
; #define PG8_BAR __builtin_amdgcn_s_barrier()
; #define PG8_SCHED __builtin_amdgcn_sched_barrier(0)
; template <class Epi, class Sched, bool ALIGN_EPI = false, bool SP2 = false>
; __device__ __forceinline__ void gemm_phase(PG8_LAS unsigned char* lds, const Gemm g, const Sched& S, const Epi& E) {
;     ...
;         for (int t = 0; t < nt; t += 2) {
;     ...
;             PG8_LDA(At, 1, 1); PG8_STAGE(PG8_SB(1, 0), b3, voffB); PG8_STAGE(PG8_SB(1, 1), b3 + hstep, voffB); PG8_STAGE(PG8_SA(1, 0), a3, voffA);
;             PG8_WAIT_V(8); PG8_WAIT_L(0); PG8_BAR; PG8_MMA(1, 0, At, B0); PG8_MMA(1, 1, At, B1); PG8_BAR; PG8_SCHED;
	s_add_i32 s30, s80, s42
	v_lshl_add_u64 v[210:211], v[210:211], 0, s[6:7]
	s_mov_b32 m0, s30
	ds_read_b128 v[182:185], v153 offset:49152
	ds_read_b128 v[186:189], v153 offset:50176
	ds_read_b128 v[190:193], v153 offset:51200
	ds_read_b128 v[194:197], v153 offset:52224
	ds_read_b128 v[198:201], v153 offset:53248
	ds_read_b128 v[202:205], v153 offset:54272
	ds_read_b128 v[206:209], v153 offset:55296
	ds_read_b128 v[214:217], v153 offset:56320
	global_load_lds_dwordx4 v[210:211], off
	s_add_i32 m0, s30, 0x2000
	s_add_u32 s30, s36, 0x158080
	v_lshl_add_u64 v[210:211], v[218:219], 0, s[6:7]
	s_addc_u32 s31, s37, 0
	s_add_i32 s36, s81, s42
	global_load_lds_dwordx4 v[210:211], off
	v_lshl_add_u64 v[210:211], s[30:31], 0, v[130:131]
	s_mov_b32 m0, s36
	s_nop 0
	global_load_lds_dwordx4 v[210:211], off
	v_lshl_add_u64 v[210:211], s[30:31], 0, v[134:135]
	s_add_i32 m0, s36, 0x2000
	s_nop 0
	global_load_lds_dwordx4 v[210:211], off
	v_lshl_add_u64 v[210:211], v[220:221], 0, s[6:7]
	s_mov_b32 m0, s50
	s_nop 0
	global_load_lds_dwordx4 v[210:211], off
	v_lshl_add_u64 v[210:211], v[222:223], 0, s[6:7]
	s_mov_b32 m0, s51
	s_nop 0
	global_load_lds_dwordx4 v[210:211], off
	s_waitcnt vmcnt(8)
	s_waitcnt lgkmcnt(0)
	s_barrier
	s_setprio 1
	s_waitcnt lgkmcnt(0)
	v_mfma_f32_16x16x32_bf16 v[60:63], v[144:147], v[182:185], v[60:63]
	v_mfma_f32_16x16x32_bf16 v[56:59], v[158:161], v[182:185], v[56:59]
	v_mfma_f32_16x16x32_bf16 v[44:47], v[144:147], v[190:193], v[44:47]
	v_mfma_f32_16x16x32_bf16 v[40:43], v[158:161], v[190:193], v[40:43]
	v_mfma_f32_16x16x32_bf16 v[28:31], v[144:147], v[198:201], v[28:31]
	v_mfma_f32_16x16x32_bf16 v[24:27], v[158:161], v[198:201], v[24:27]
	v_mfma_f32_16x16x32_bf16 v[12:15], v[144:147], v[206:209], v[12:15]
	v_mfma_f32_16x16x32_bf16 v[8:11], v[158:161], v[206:209], v[8:11]
	v_mfma_f32_16x16x32_bf16 v[60:63], v[154:157], v[186:189], v[60:63]
	v_mfma_f32_16x16x32_bf16 v[56:59], v[162:165], v[186:189], v[56:59]
	v_mfma_f32_16x16x32_bf16 v[44:47], v[154:157], v[194:197], v[44:47]
	v_mfma_f32_16x16x32_bf16 v[40:43], v[162:165], v[194:197], v[40:43]
	v_mfma_f32_16x16x32_bf16 v[28:31], v[154:157], v[202:205], v[28:31]
	v_mfma_f32_16x16x32_bf16 v[24:27], v[162:165], v[202:205], v[24:27]
	v_mfma_f32_16x16x32_bf16 v[12:15], v[154:157], v[214:217], v[12:15]
	v_mfma_f32_16x16x32_bf16 v[8:11], v[162:165], v[214:217], v[8:11]
	s_setprio 0
	s_setprio 1
	v_mfma_f32_16x16x32_bf16 v[52:55], v[166:169], v[182:185], v[52:55]
	v_mfma_f32_16x16x32_bf16 v[48:51], v[174:177], v[182:185], v[48:51]
	v_mfma_f32_16x16x32_bf16 v[36:39], v[166:169], v[190:193], v[36:39]
	v_mfma_f32_16x16x32_bf16 v[32:35], v[174:177], v[190:193], v[32:35]
	v_mfma_f32_16x16x32_bf16 v[20:23], v[166:169], v[198:201], v[20:23]
	v_mfma_f32_16x16x32_bf16 v[16:19], v[174:177], v[198:201], v[16:19]
	v_mfma_f32_16x16x32_bf16 v[4:7], v[166:169], v[206:209], v[4:7]
	v_mfma_f32_16x16x32_bf16 v[0:3], v[174:177], v[206:209], v[0:3]
	v_mfma_f32_16x16x32_bf16 v[52:55], v[170:173], v[186:189], v[52:55]
	v_mfma_f32_16x16x32_bf16 v[48:51], v[178:181], v[186:189], v[48:51]
	v_mfma_f32_16x16x32_bf16 v[36:39], v[170:173], v[194:197], v[36:39]
	v_mfma_f32_16x16x32_bf16 v[32:35], v[178:181], v[194:197], v[32:35]
	v_mfma_f32_16x16x32_bf16 v[20:23], v[170:173], v[202:205], v[20:23]
	v_mfma_f32_16x16x32_bf16 v[16:19], v[178:181], v[202:205], v[16:19]
	v_mfma_f32_16x16x32_bf16 v[4:7], v[170:173], v[214:217], v[4:7]
	v_mfma_f32_16x16x32_bf16 v[0:3], v[178:181], v[214:217], v[0:3]
	s_setprio 0
	s_add_u32 s77, s77, 0x100
	s_addc_u32 s78, s78, 0
	s_cmp_ge_u32 s79, s9
	s_mov_b64 s[30:31], s[34:35]
	s_mov_b32 s36, s79
	s_barrier
	s_cbranch_scc0 .LBB0_976
